# v5 (S1 re-deal guarded on grid 256) + LoRA-up GEMM sigmoid epilogue: the two bias vectors loaded once per unit instead of in each of 16 chunks with vmcnt(0)
# speedup vs baseline: 1.0197x; 1.0006x over previous
.LBB0_1160:
	s_cmp_eq_u32 s85, 7
	s_cbranch_scc0 .Lmy_s1_norestore
	s_cmpk_eq_u32 s50, 0xa0
	s_cbranch_scc1 .Lmy_s1_dorestore
	s_cmpk_eq_u32 s50, 0x400
	s_cbranch_scc0 .Lmy_s1_norestore
.Lmy_s1_dorestore:
	v_readlane_b32 s2, v254, 34
	s_movk_i32 s50, 0x100
	s_lshr_b32 s2, s2, 3
	s_lshr_b32 vcc_lo, s2, 3
	v_writelane_b32 v252, vcc_lo, 40
	s_and_b32 vcc_lo, s2, 7
	v_writelane_b32 v252, vcc_lo, 43

.LBB0_1171:
	s_cmp_eq_u32 s85, 7
	s_cbranch_scc0 .Lmy_s1_skip
	s_cmpk_eq_u32 s50, 0x100
	s_cbranch_scc0 .Lmy_s1_skip
	v_readlane_b32 s5, v254, 34
	s_lshr_b32 s5, s5, 3
	s_cmpk_lt_u32 s5, 0xa0
	s_cbranch_scc0 .Lmy_s1_hi
	s_add_i32 s2, s5, 0x60
	s_movk_i32 s50, 0xa0
	s_branch .Lmy_s1_setlanes

.LBB0_1211:
	v_lshlrev_b32_e32 v0, 2, v138
	v_lshl_add_u64 v[144:145], s[96:97], 0, v[0:1]
	s_cmp_lt_i32 s5, 3
	s_mov_b64 s[16:17], -1
	s_cbranch_scc1 .LBB0_1217
	s_cmp_gt_i32 s5, 3
	s_cbranch_scc0 .LBB0_1214
	global_load_dwordx4 v[182:185], v[144:145], off offset:16
	global_load_dwordx4 v[178:181], v[144:145], off
	global_load_dwordx4 v[190:193], v[144:145], off offset:528
	global_load_dwordx4 v[186:189], v[144:145], off offset:512
	s_waitcnt vmcnt(0)
	v_mov_b32_e32 v152, v182
	v_mov_b32_e32 v153, v183
	v_mov_b32_e32 v154, v184
	v_mov_b32_e32 v155, v185
	v_mov_b32_e32 v156, v178
	v_mov_b32_e32 v157, v179
	v_mov_b32_e32 v158, v180
	v_mov_b32_e32 v159, v181
	v_add_f32_e32 v0, v126, v156
	v_mul_f32_e32 v0, 0xbfb8aa3b, v0
	v_exp_f32_e32 v160, v0
	v_add_f32_e32 v0, v127, v157
	v_mul_f32_e32 v0, 0xbfb8aa3b, v0
	v_exp_f32_e32 v161, v0
	v_add_f32_e32 v0, v128, v158
	v_mul_f32_e32 v0, 0xbfb8aa3b, v0
	v_exp_f32_e32 v158, v0
	v_add_f32_e32 v0, v129, v159
	v_mul_f32_e32 v0, 0xbfb8aa3b, v0
	v_exp_f32_e32 v159, v0
	v_add_f32_e32 v0, v122, v152
	v_mul_f32_e32 v0, 0xbfb8aa3b, v0
	v_exp_f32_e32 v156, v0
	v_add_f32_e32 v0, v123, v153
	v_mul_f32_e32 v0, 0xbfb8aa3b, v0
	v_exp_f32_e32 v157, v0
	v_add_f32_e32 v0, v124, v154
	v_mul_f32_e32 v0, 0xbfb8aa3b, v0
	v_exp_f32_e32 v152, v0
	v_add_f32_e32 v0, v125, v155
	v_mul_f32_e32 v0, 0xbfb8aa3b, v0
	v_pk_add_f32 v[154:155], v[160:161], 1.0 op_sel_hi:[1,0]
	v_exp_f32_e32 v153, v0
	v_div_scale_f32 v0, s[16:17], v155, v155, 1.0
	v_rcp_f32_e32 v147, v0
	v_pk_add_f32 v[158:159], v[158:159], 1.0 op_sel_hi:[1,0]
	v_pk_add_f32 v[156:157], v[156:157], 1.0 op_sel_hi:[1,0]
	v_pk_add_f32 v[152:153], v[152:153], 1.0 op_sel_hi:[1,0]
	v_fma_f32 v160, -v0, v147, 1.0
	v_fmac_f32_e32 v147, v160, v147
	v_div_scale_f32 v160, vcc, 1.0, v155, 1.0
	v_mul_f32_e32 v161, v160, v147
	v_fma_f32 v162, -v0, v161, v160
	v_fmac_f32_e32 v161, v162, v147
	v_fma_f32 v0, -v0, v161, v160
	v_div_fmas_f32 v0, v0, v147, v161
	v_div_fixup_f32 v155, v0, v155, 1.0
	v_div_scale_f32 v0, s[16:17], v154, v154, 1.0
	v_rcp_f32_e32 v147, v0
	s_nop 0
	v_fma_f32 v160, -v0, v147, 1.0
	v_fmac_f32_e32 v147, v160, v147
	v_div_scale_f32 v160, vcc, 1.0, v154, 1.0
	v_mul_f32_e32 v161, v160, v147
	v_fma_f32 v162, -v0, v161, v160
	v_fmac_f32_e32 v161, v162, v147
	v_fma_f32 v0, -v0, v161, v160
	v_div_fmas_f32 v0, v0, v147, v161
	v_div_fixup_f32 v154, v0, v154, 1.0
	v_div_scale_f32 v0, s[16:17], v159, v159, 1.0
	v_rcp_f32_e32 v147, v0
	s_nop 0
	v_fma_f32 v160, -v0, v147, 1.0
	v_fmac_f32_e32 v147, v160, v147
	v_div_scale_f32 v160, vcc, 1.0, v159, 1.0
	v_mul_f32_e32 v161, v160, v147
	v_fma_f32 v162, -v0, v161, v160
	v_fmac_f32_e32 v161, v162, v147
	v_fma_f32 v0, -v0, v161, v160
	v_div_fmas_f32 v0, v0, v147, v161
	v_div_fixup_f32 v159, v0, v159, 1.0
	v_div_scale_f32 v0, s[16:17], v158, v158, 1.0
	v_rcp_f32_e32 v147, v0
	s_nop 0
	v_fma_f32 v160, -v0, v147, 1.0
	v_fmac_f32_e32 v147, v160, v147
	v_div_scale_f32 v160, vcc, 1.0, v158, 1.0
	v_mul_f32_e32 v161, v160, v147
	v_fma_f32 v162, -v0, v161, v160
	v_fmac_f32_e32 v161, v162, v147
	v_fma_f32 v0, -v0, v161, v160
	v_div_fmas_f32 v0, v0, v147, v161
	v_div_fixup_f32 v158, v0, v158, 1.0
	v_div_scale_f32 v0, s[16:17], v157, v157, 1.0
	v_rcp_f32_e32 v147, v0
	s_nop 0
	v_fma_f32 v160, -v0, v147, 1.0
	v_fmac_f32_e32 v147, v160, v147
	v_div_scale_f32 v160, vcc, 1.0, v157, 1.0
	v_mul_f32_e32 v161, v160, v147
	v_fma_f32 v162, -v0, v161, v160
	v_fmac_f32_e32 v161, v162, v147
	v_fma_f32 v0, -v0, v161, v160
	v_div_fmas_f32 v0, v0, v147, v161
	v_div_fixup_f32 v157, v0, v157, 1.0
	v_div_scale_f32 v0, s[16:17], v156, v156, 1.0
	v_rcp_f32_e32 v147, v0
	s_nop 0
	v_fma_f32 v160, -v0, v147, 1.0
	v_fmac_f32_e32 v147, v160, v147
	v_div_scale_f32 v160, vcc, 1.0, v156, 1.0
	v_mul_f32_e32 v161, v160, v147
	v_fma_f32 v162, -v0, v161, v160
	v_fmac_f32_e32 v161, v162, v147
	v_fma_f32 v0, -v0, v161, v160
	v_div_fmas_f32 v0, v0, v147, v161
	v_div_fixup_f32 v156, v0, v156, 1.0
	v_div_scale_f32 v0, s[16:17], v153, v153, 1.0
	v_rcp_f32_e32 v147, v0
	s_nop 0
	v_fma_f32 v160, -v0, v147, 1.0
	v_fmac_f32_e32 v147, v160, v147
	v_div_scale_f32 v160, vcc, 1.0, v153, 1.0
	v_mul_f32_e32 v161, v160, v147
	v_fma_f32 v162, -v0, v161, v160
	v_fmac_f32_e32 v161, v162, v147
	v_fma_f32 v0, -v0, v161, v160
	v_div_fmas_f32 v0, v0, v147, v161
	v_div_fixup_f32 v153, v0, v153, 1.0
	v_div_scale_f32 v0, s[16:17], v152, v152, 1.0
	v_rcp_f32_e32 v147, v0
	s_mov_b64 s[16:17], 0
	v_fma_f32 v160, -v0, v147, 1.0
	v_fmac_f32_e32 v147, v160, v147
	v_div_scale_f32 v160, vcc, 1.0, v152, 1.0
	v_mul_f32_e32 v161, v160, v147
	v_fma_f32 v162, -v0, v161, v160
	v_fmac_f32_e32 v161, v162, v147
	v_fma_f32 v0, -v0, v161, v160
	v_div_fmas_f32 v0, v0, v147, v161
	v_div_fixup_f32 v152, v0, v152, 1.0
	v_pk_mul_f32 v[162:163], s[18:19], v[152:153] op_sel_hi:[0,1]
	v_pk_mul_f32 v[160:161], s[18:19], v[156:157] op_sel_hi:[0,1]
	v_pk_mul_f32 v[156:157], s[18:19], v[158:159] op_sel_hi:[0,1]
	v_pk_mul_f32 v[152:153], s[18:19], v[154:155] op_sel_hi:[0,1]

.LBB0_1227:
	s_cmp_gt_i32 s19, 3
	s_mov_b64 s[16:17], -1
	s_cbranch_scc0 .LBB0_1229
	v_mov_b32_e32 v122, v190
	v_mov_b32_e32 v123, v191
	v_mov_b32_e32 v124, v192
	v_mov_b32_e32 v125, v193
	v_mov_b32_e32 v126, v186
	v_mov_b32_e32 v127, v187
	v_mov_b32_e32 v128, v188
	v_mov_b32_e32 v129, v189
	v_add_f32_e32 v122, v114, v122
	v_add_f32_e32 v126, v118, v126
	v_mul_f32_e32 v126, 0xbfb8aa3b, v126
	v_exp_f32_e32 v152, v126
	v_add_f32_e32 v126, v119, v127
	v_mul_f32_e32 v126, 0xbfb8aa3b, v126
	v_exp_f32_e32 v153, v126
	v_add_f32_e32 v126, v120, v128
	v_mul_f32_e32 v126, 0xbfb8aa3b, v126
	v_exp_f32_e32 v128, v126
	v_add_f32_e32 v126, v121, v129
	v_mul_f32_e32 v126, 0xbfb8aa3b, v126
	v_mul_f32_e32 v122, 0xbfb8aa3b, v122
	v_exp_f32_e32 v129, v126
	v_exp_f32_e32 v126, v122
	v_add_f32_e32 v122, v115, v123
	v_mul_f32_e32 v122, 0xbfb8aa3b, v122
	v_exp_f32_e32 v127, v122
	v_add_f32_e32 v122, v116, v124
	v_add_f32_e32 v123, v117, v125
	v_pk_add_f32 v[124:125], v[152:153], 1.0 op_sel_hi:[1,0]
	v_pk_add_f32 v[128:129], v[128:129], 1.0 op_sel_hi:[1,0]
	v_div_scale_f32 v152, s[16:17], v125, v125, 1.0
	v_rcp_f32_e32 v153, v152
	v_pk_add_f32 v[126:127], v[126:127], 1.0 op_sel_hi:[1,0]
	v_mul_f32_e32 v122, 0xbfb8aa3b, v122
	v_mul_f32_e32 v123, 0xbfb8aa3b, v123
	v_fma_f32 v155, -v152, v153, 1.0
	v_fmac_f32_e32 v153, v155, v153
	v_div_scale_f32 v155, vcc, 1.0, v125, 1.0
	v_mul_f32_e32 v156, v155, v153
	v_fma_f32 v157, -v152, v156, v155
	v_fmac_f32_e32 v156, v157, v153
	v_fma_f32 v152, -v152, v156, v155
	v_div_fmas_f32 v152, v152, v153, v156
	v_div_fixup_f32 v125, v152, v125, 1.0
	v_div_scale_f32 v152, s[16:17], v124, v124, 1.0
	v_rcp_f32_e32 v153, v152
	v_exp_f32_e32 v122, v122
	v_exp_f32_e32 v123, v123
	v_fma_f32 v155, -v152, v153, 1.0
	v_fmac_f32_e32 v153, v155, v153
	v_div_scale_f32 v155, vcc, 1.0, v124, 1.0
	v_mul_f32_e32 v156, v155, v153
	v_fma_f32 v157, -v152, v156, v155
	v_fmac_f32_e32 v156, v157, v153
	v_fma_f32 v152, -v152, v156, v155
	v_div_fmas_f32 v152, v152, v153, v156
	v_div_fixup_f32 v124, v152, v124, 1.0
	v_div_scale_f32 v152, s[16:17], v129, v129, 1.0
	v_rcp_f32_e32 v153, v152
	v_pk_add_f32 v[122:123], v[122:123], 1.0 op_sel_hi:[1,0]
	v_pk_mul_f32 v[124:125], s[18:19], v[124:125] op_sel_hi:[0,1]
	v_fma_f32 v155, -v152, v153, 1.0
	v_fmac_f32_e32 v153, v155, v153
	v_div_scale_f32 v155, vcc, 1.0, v129, 1.0
	v_mul_f32_e32 v156, v155, v153
	v_fma_f32 v157, -v152, v156, v155
	v_fmac_f32_e32 v156, v157, v153
	v_fma_f32 v152, -v152, v156, v155
	v_div_fmas_f32 v152, v152, v153, v156
	v_div_fixup_f32 v129, v152, v129, 1.0
	v_div_scale_f32 v152, s[16:17], v128, v128, 1.0
	v_rcp_f32_e32 v153, v152
	s_nop 0
	v_fma_f32 v155, -v152, v153, 1.0
	v_fmac_f32_e32 v153, v155, v153
	v_div_scale_f32 v155, vcc, 1.0, v128, 1.0
	v_mul_f32_e32 v156, v155, v153
	v_fma_f32 v157, -v152, v156, v155
	v_fmac_f32_e32 v156, v157, v153
	v_fma_f32 v152, -v152, v156, v155
	v_div_fmas_f32 v152, v152, v153, v156
	v_div_fixup_f32 v128, v152, v128, 1.0
	v_div_scale_f32 v152, s[16:17], v127, v127, 1.0
	v_rcp_f32_e32 v153, v152
	v_pk_mul_f32 v[128:129], s[18:19], v[128:129] op_sel_hi:[0,1]
	v_fma_f32 v155, -v152, v153, 1.0
	v_fmac_f32_e32 v153, v155, v153
	v_div_scale_f32 v155, vcc, 1.0, v127, 1.0
	v_mul_f32_e32 v156, v155, v153
	v_fma_f32 v157, -v152, v156, v155
	v_fmac_f32_e32 v156, v157, v153
	v_fma_f32 v152, -v152, v156, v155
	v_div_fmas_f32 v152, v152, v153, v156
	v_div_fixup_f32 v127, v152, v127, 1.0
	v_div_scale_f32 v152, s[16:17], v126, v126, 1.0
	v_rcp_f32_e32 v153, v152
	s_nop 0
	v_fma_f32 v155, -v152, v153, 1.0
	v_fmac_f32_e32 v153, v155, v153
	v_div_scale_f32 v155, vcc, 1.0, v126, 1.0
	v_mul_f32_e32 v156, v155, v153
	v_fma_f32 v157, -v152, v156, v155
	v_fmac_f32_e32 v156, v157, v153
	v_fma_f32 v152, -v152, v156, v155
	v_div_fmas_f32 v152, v152, v153, v156
	v_div_fixup_f32 v126, v152, v126, 1.0
	v_div_scale_f32 v152, s[16:17], v123, v123, 1.0
	v_rcp_f32_e32 v153, v152
	v_pk_mul_f32 v[126:127], s[18:19], v[126:127] op_sel_hi:[0,1]
	v_fma_f32 v155, -v152, v153, 1.0
	v_fmac_f32_e32 v153, v155, v153
	v_div_scale_f32 v155, vcc, 1.0, v123, 1.0
	v_mul_f32_e32 v156, v155, v153
	v_fma_f32 v157, -v152, v156, v155
	v_fmac_f32_e32 v156, v157, v153
	v_fma_f32 v152, -v152, v156, v155
	v_div_fmas_f32 v152, v152, v153, v156
	v_div_fixup_f32 v123, v152, v123, 1.0
	v_div_scale_f32 v152, s[16:17], v122, v122, 1.0
	v_rcp_f32_e32 v153, v152
	s_nop 0
	v_fma_f32 v155, -v152, v153, 1.0
	v_fmac_f32_e32 v153, v155, v153
	v_div_scale_f32 v155, vcc, 1.0, v122, 1.0
	v_mul_f32_e32 v156, v155, v153
	v_fma_f32 v157, -v152, v156, v155
	v_fmac_f32_e32 v156, v157, v153
	v_fma_f32 v152, -v152, v156, v155
	v_div_fmas_f32 v152, v152, v153, v156
	v_div_fixup_f32 v122, v152, v122, 1.0
	v_pk_mul_f32 v[122:123], s[18:19], v[122:123] op_sel_hi:[0,1]
	s_cbranch_execnz .LBB0_1233
	s_branch .LBB0_1230

.LBB0_1239:
	s_cmp_lt_i32 s5, 3
	s_mov_b64 s[16:17], -1
	s_cbranch_scc1 .LBB0_1245
	s_cmp_gt_i32 s5, 3
	s_cbranch_scc0 .LBB0_1242
	v_mov_b32_e32 v116, v182
	v_mov_b32_e32 v117, v183
	v_mov_b32_e32 v118, v184
	v_mov_b32_e32 v119, v185
	v_mov_b32_e32 v120, v178
	v_mov_b32_e32 v121, v179
	v_mov_b32_e32 v122, v180
	v_mov_b32_e32 v123, v181
	v_add_f32_e32 v116, v106, v116
	v_add_f32_e32 v120, v110, v120
	v_mul_f32_e32 v120, 0xbfb8aa3b, v120
	v_exp_f32_e32 v124, v120
	v_add_f32_e32 v120, v111, v121
	v_mul_f32_e32 v120, 0xbfb8aa3b, v120
	v_exp_f32_e32 v125, v120
	v_add_f32_e32 v120, v112, v122
	v_mul_f32_e32 v120, 0xbfb8aa3b, v120
	v_exp_f32_e32 v122, v120
	v_add_f32_e32 v120, v113, v123
	v_mul_f32_e32 v120, 0xbfb8aa3b, v120
	v_mul_f32_e32 v116, 0xbfb8aa3b, v116
	v_exp_f32_e32 v123, v120
	v_exp_f32_e32 v120, v116
	v_add_f32_e32 v116, v107, v117
	v_mul_f32_e32 v116, 0xbfb8aa3b, v116
	v_exp_f32_e32 v121, v116
	v_add_f32_e32 v116, v108, v118
	v_add_f32_e32 v117, v109, v119
	v_pk_add_f32 v[118:119], v[124:125], 1.0 op_sel_hi:[1,0]
	v_pk_add_f32 v[122:123], v[122:123], 1.0 op_sel_hi:[1,0]
	v_div_scale_f32 v124, s[16:17], v119, v119, 1.0
	v_rcp_f32_e32 v125, v124
	v_pk_add_f32 v[120:121], v[120:121], 1.0 op_sel_hi:[1,0]
	v_mul_f32_e32 v116, 0xbfb8aa3b, v116
	v_mul_f32_e32 v117, 0xbfb8aa3b, v117
	v_fma_f32 v126, -v124, v125, 1.0
	v_fmac_f32_e32 v125, v126, v125
	v_div_scale_f32 v126, vcc, 1.0, v119, 1.0
	v_mul_f32_e32 v127, v126, v125
	v_fma_f32 v129, -v124, v127, v126
	v_fmac_f32_e32 v127, v129, v125
	v_fma_f32 v124, -v124, v127, v126
	v_div_fmas_f32 v124, v124, v125, v127
	v_div_fixup_f32 v119, v124, v119, 1.0
	v_div_scale_f32 v124, s[16:17], v118, v118, 1.0
	v_rcp_f32_e32 v125, v124
	v_exp_f32_e32 v116, v116
	v_exp_f32_e32 v117, v117
	v_fma_f32 v126, -v124, v125, 1.0
	v_fmac_f32_e32 v125, v126, v125
	v_div_scale_f32 v126, vcc, 1.0, v118, 1.0
	v_mul_f32_e32 v127, v126, v125
	v_fma_f32 v129, -v124, v127, v126
	v_fmac_f32_e32 v127, v129, v125
	v_fma_f32 v124, -v124, v127, v126
	v_div_fmas_f32 v124, v124, v125, v127
	v_div_fixup_f32 v118, v124, v118, 1.0
	v_div_scale_f32 v124, s[16:17], v123, v123, 1.0
	v_rcp_f32_e32 v125, v124
	v_pk_add_f32 v[116:117], v[116:117], 1.0 op_sel_hi:[1,0]
	v_fma_f32 v126, -v124, v125, 1.0
	v_fmac_f32_e32 v125, v126, v125
	v_div_scale_f32 v126, vcc, 1.0, v123, 1.0
	v_mul_f32_e32 v127, v126, v125
	v_fma_f32 v129, -v124, v127, v126
	v_fmac_f32_e32 v127, v129, v125
	v_fma_f32 v124, -v124, v127, v126
	v_div_fmas_f32 v124, v124, v125, v127
	v_div_fixup_f32 v123, v124, v123, 1.0
	v_div_scale_f32 v124, s[16:17], v122, v122, 1.0
	v_rcp_f32_e32 v125, v124
	s_nop 0
	v_fma_f32 v126, -v124, v125, 1.0
	v_fmac_f32_e32 v125, v126, v125
	v_div_scale_f32 v126, vcc, 1.0, v122, 1.0
	v_mul_f32_e32 v127, v126, v125
	v_fma_f32 v129, -v124, v127, v126
	v_fmac_f32_e32 v127, v129, v125
	v_fma_f32 v124, -v124, v127, v126
	v_div_fmas_f32 v124, v124, v125, v127
	v_div_fixup_f32 v122, v124, v122, 1.0
	v_div_scale_f32 v124, s[16:17], v121, v121, 1.0
	v_rcp_f32_e32 v125, v124
	s_nop 0
	v_fma_f32 v126, -v124, v125, 1.0
	v_fmac_f32_e32 v125, v126, v125
	v_div_scale_f32 v126, vcc, 1.0, v121, 1.0
	v_mul_f32_e32 v127, v126, v125
	v_fma_f32 v129, -v124, v127, v126
	v_fmac_f32_e32 v127, v129, v125
	v_fma_f32 v124, -v124, v127, v126
	v_div_fmas_f32 v124, v124, v125, v127
	v_div_fixup_f32 v121, v124, v121, 1.0
	v_div_scale_f32 v124, s[16:17], v120, v120, 1.0
	v_rcp_f32_e32 v125, v124
	s_nop 0
	v_fma_f32 v126, -v124, v125, 1.0
	v_fmac_f32_e32 v125, v126, v125
	v_div_scale_f32 v126, vcc, 1.0, v120, 1.0
	v_mul_f32_e32 v127, v126, v125
	v_fma_f32 v129, -v124, v127, v126
	v_fmac_f32_e32 v127, v129, v125
	v_fma_f32 v124, -v124, v127, v126
	v_div_fmas_f32 v124, v124, v125, v127
	v_div_fixup_f32 v120, v124, v120, 1.0
	v_div_scale_f32 v124, s[16:17], v117, v117, 1.0
	v_rcp_f32_e32 v125, v124
	s_nop 0
	v_fma_f32 v126, -v124, v125, 1.0
	v_fmac_f32_e32 v125, v126, v125
	v_div_scale_f32 v126, vcc, 1.0, v117, 1.0
	v_mul_f32_e32 v127, v126, v125
	v_fma_f32 v129, -v124, v127, v126
	v_fmac_f32_e32 v127, v129, v125
	v_fma_f32 v124, -v124, v127, v126
	v_div_fmas_f32 v124, v124, v125, v127
	v_div_fixup_f32 v117, v124, v117, 1.0
	v_div_scale_f32 v124, s[16:17], v116, v116, 1.0
	v_rcp_f32_e32 v125, v124
	s_mov_b64 s[16:17], 0
	v_fma_f32 v126, -v124, v125, 1.0
	v_fmac_f32_e32 v125, v126, v125
	v_div_scale_f32 v126, vcc, 1.0, v116, 1.0
	v_mul_f32_e32 v127, v126, v125
	v_fma_f32 v129, -v124, v127, v126
	v_fmac_f32_e32 v127, v129, v125
	v_fma_f32 v124, -v124, v127, v126
	v_div_fmas_f32 v124, v124, v125, v127
	v_div_fixup_f32 v116, v124, v116, 1.0
	v_pk_mul_f32 v[126:127], s[18:19], v[116:117] op_sel_hi:[0,1]
	v_pk_mul_f32 v[124:125], s[18:19], v[120:121] op_sel_hi:[0,1]
	v_pk_mul_f32 v[120:121], s[18:19], v[122:123] op_sel_hi:[0,1]
	v_pk_mul_f32 v[116:117], s[18:19], v[118:119] op_sel_hi:[0,1]

.LBB0_1255:
	s_cmp_gt_i32 s19, 3
	s_mov_b64 s[16:17], -1
	s_cbranch_scc0 .LBB0_1257
	v_mov_b32_e32 v106, v190
	v_mov_b32_e32 v107, v191
	v_mov_b32_e32 v108, v192
	v_mov_b32_e32 v109, v193
	v_mov_b32_e32 v110, v186
	v_mov_b32_e32 v111, v187
	v_mov_b32_e32 v112, v188
	v_mov_b32_e32 v113, v189
	v_add_f32_e32 v106, v98, v106
	v_add_f32_e32 v110, v102, v110
	v_mul_f32_e32 v110, 0xbfb8aa3b, v110
	v_exp_f32_e32 v116, v110
	v_add_f32_e32 v110, v103, v111
	v_mul_f32_e32 v110, 0xbfb8aa3b, v110
	v_exp_f32_e32 v117, v110
	v_add_f32_e32 v110, v104, v112
	v_mul_f32_e32 v110, 0xbfb8aa3b, v110
	v_exp_f32_e32 v112, v110
	v_add_f32_e32 v110, v105, v113
	v_mul_f32_e32 v110, 0xbfb8aa3b, v110
	v_mul_f32_e32 v106, 0xbfb8aa3b, v106
	v_exp_f32_e32 v113, v110
	v_exp_f32_e32 v110, v106
	v_add_f32_e32 v106, v99, v107
	v_mul_f32_e32 v106, 0xbfb8aa3b, v106
	v_exp_f32_e32 v111, v106
	v_add_f32_e32 v106, v100, v108
	v_add_f32_e32 v107, v101, v109
	v_pk_add_f32 v[108:109], v[116:117], 1.0 op_sel_hi:[1,0]
	v_pk_add_f32 v[112:113], v[112:113], 1.0 op_sel_hi:[1,0]
	v_div_scale_f32 v116, s[16:17], v109, v109, 1.0
	v_rcp_f32_e32 v117, v116
	v_pk_add_f32 v[110:111], v[110:111], 1.0 op_sel_hi:[1,0]
	v_mul_f32_e32 v106, 0xbfb8aa3b, v106
	v_mul_f32_e32 v107, 0xbfb8aa3b, v107
	v_fma_f32 v118, -v116, v117, 1.0
	v_fmac_f32_e32 v117, v118, v117
	v_div_scale_f32 v118, vcc, 1.0, v109, 1.0
	v_mul_f32_e32 v119, v118, v117
	v_fma_f32 v120, -v116, v119, v118
	v_fmac_f32_e32 v119, v120, v117
	v_fma_f32 v116, -v116, v119, v118
	v_div_fmas_f32 v116, v116, v117, v119
	v_div_fixup_f32 v109, v116, v109, 1.0
	v_div_scale_f32 v116, s[16:17], v108, v108, 1.0
	v_rcp_f32_e32 v117, v116
	v_exp_f32_e32 v106, v106
	v_exp_f32_e32 v107, v107
	v_fma_f32 v118, -v116, v117, 1.0
	v_fmac_f32_e32 v117, v118, v117
	v_div_scale_f32 v118, vcc, 1.0, v108, 1.0
	v_mul_f32_e32 v119, v118, v117
	v_fma_f32 v120, -v116, v119, v118
	v_fmac_f32_e32 v119, v120, v117
	v_fma_f32 v116, -v116, v119, v118
	v_div_fmas_f32 v116, v116, v117, v119
	v_div_fixup_f32 v108, v116, v108, 1.0
	v_div_scale_f32 v116, s[16:17], v113, v113, 1.0
	v_rcp_f32_e32 v117, v116
	v_pk_add_f32 v[106:107], v[106:107], 1.0 op_sel_hi:[1,0]
	v_pk_mul_f32 v[108:109], s[18:19], v[108:109] op_sel_hi:[0,1]
	v_fma_f32 v118, -v116, v117, 1.0
	v_fmac_f32_e32 v117, v118, v117
	v_div_scale_f32 v118, vcc, 1.0, v113, 1.0
	v_mul_f32_e32 v119, v118, v117
	v_fma_f32 v120, -v116, v119, v118
	v_fmac_f32_e32 v119, v120, v117
	v_fma_f32 v116, -v116, v119, v118
	v_div_fmas_f32 v116, v116, v117, v119
	v_div_fixup_f32 v113, v116, v113, 1.0
	v_div_scale_f32 v116, s[16:17], v112, v112, 1.0
	v_rcp_f32_e32 v117, v116
	s_nop 0
	v_fma_f32 v118, -v116, v117, 1.0
	v_fmac_f32_e32 v117, v118, v117
	v_div_scale_f32 v118, vcc, 1.0, v112, 1.0
	v_mul_f32_e32 v119, v118, v117
	v_fma_f32 v120, -v116, v119, v118
	v_fmac_f32_e32 v119, v120, v117
	v_fma_f32 v116, -v116, v119, v118
	v_div_fmas_f32 v116, v116, v117, v119
	v_div_fixup_f32 v112, v116, v112, 1.0
	v_div_scale_f32 v116, s[16:17], v111, v111, 1.0
	v_rcp_f32_e32 v117, v116
	v_pk_mul_f32 v[112:113], s[18:19], v[112:113] op_sel_hi:[0,1]
	v_fma_f32 v118, -v116, v117, 1.0
	v_fmac_f32_e32 v117, v118, v117
	v_div_scale_f32 v118, vcc, 1.0, v111, 1.0
	v_mul_f32_e32 v119, v118, v117
	v_fma_f32 v120, -v116, v119, v118
	v_fmac_f32_e32 v119, v120, v117
	v_fma_f32 v116, -v116, v119, v118
	v_div_fmas_f32 v116, v116, v117, v119
	v_div_fixup_f32 v111, v116, v111, 1.0
	v_div_scale_f32 v116, s[16:17], v110, v110, 1.0
	v_rcp_f32_e32 v117, v116
	s_nop 0
	v_fma_f32 v118, -v116, v117, 1.0
	v_fmac_f32_e32 v117, v118, v117
	v_div_scale_f32 v118, vcc, 1.0, v110, 1.0
	v_mul_f32_e32 v119, v118, v117
	v_fma_f32 v120, -v116, v119, v118
	v_fmac_f32_e32 v119, v120, v117
	v_fma_f32 v116, -v116, v119, v118
	v_div_fmas_f32 v116, v116, v117, v119
	v_div_fixup_f32 v110, v116, v110, 1.0
	v_div_scale_f32 v116, s[16:17], v107, v107, 1.0
	v_rcp_f32_e32 v117, v116
	v_pk_mul_f32 v[110:111], s[18:19], v[110:111] op_sel_hi:[0,1]
	v_fma_f32 v118, -v116, v117, 1.0
	v_fmac_f32_e32 v117, v118, v117
	v_div_scale_f32 v118, vcc, 1.0, v107, 1.0
	v_mul_f32_e32 v119, v118, v117
	v_fma_f32 v120, -v116, v119, v118
	v_fmac_f32_e32 v119, v120, v117
	v_fma_f32 v116, -v116, v119, v118
	v_div_fmas_f32 v116, v116, v117, v119
	v_div_fixup_f32 v107, v116, v107, 1.0
	v_div_scale_f32 v116, s[16:17], v106, v106, 1.0
	v_rcp_f32_e32 v117, v116
	s_nop 0
	v_fma_f32 v118, -v116, v117, 1.0
	v_fmac_f32_e32 v117, v118, v117
	v_div_scale_f32 v118, vcc, 1.0, v106, 1.0
	v_mul_f32_e32 v119, v118, v117
	v_fma_f32 v120, -v116, v119, v118
	v_fmac_f32_e32 v119, v120, v117
	v_fma_f32 v116, -v116, v119, v118
	v_div_fmas_f32 v116, v116, v117, v119
	v_div_fixup_f32 v106, v116, v106, 1.0
	v_pk_mul_f32 v[106:107], s[18:19], v[106:107] op_sel_hi:[0,1]
	s_cbranch_execnz .LBB0_1261
	s_branch .LBB0_1258

.LBB0_1267:
	s_cmp_lt_i32 s5, 3
	s_mov_b64 s[16:17], -1
	s_cbranch_scc1 .LBB0_1273
	s_cmp_gt_i32 s5, 3
	s_cbranch_scc0 .LBB0_1270
	v_mov_b32_e32 v100, v182
	v_mov_b32_e32 v101, v183
	v_mov_b32_e32 v102, v184
	v_mov_b32_e32 v103, v185
	v_mov_b32_e32 v104, v178
	v_mov_b32_e32 v105, v179
	v_mov_b32_e32 v106, v180
	v_mov_b32_e32 v107, v181
	v_add_f32_e32 v100, v90, v100
	v_add_f32_e32 v104, v94, v104
	v_mul_f32_e32 v104, 0xbfb8aa3b, v104
	v_exp_f32_e32 v108, v104
	v_add_f32_e32 v104, v95, v105
	v_mul_f32_e32 v104, 0xbfb8aa3b, v104
	v_exp_f32_e32 v109, v104
	v_add_f32_e32 v104, v96, v106
	v_mul_f32_e32 v104, 0xbfb8aa3b, v104
	v_exp_f32_e32 v106, v104
	v_add_f32_e32 v104, v97, v107
	v_mul_f32_e32 v104, 0xbfb8aa3b, v104
	v_mul_f32_e32 v100, 0xbfb8aa3b, v100
	v_exp_f32_e32 v107, v104
	v_exp_f32_e32 v104, v100
	v_add_f32_e32 v100, v91, v101
	v_mul_f32_e32 v100, 0xbfb8aa3b, v100
	v_exp_f32_e32 v105, v100
	v_add_f32_e32 v100, v92, v102
	v_add_f32_e32 v101, v93, v103
	v_pk_add_f32 v[102:103], v[108:109], 1.0 op_sel_hi:[1,0]
	v_pk_add_f32 v[106:107], v[106:107], 1.0 op_sel_hi:[1,0]
	v_div_scale_f32 v108, s[16:17], v103, v103, 1.0
	v_rcp_f32_e32 v109, v108
	v_pk_add_f32 v[104:105], v[104:105], 1.0 op_sel_hi:[1,0]
	v_mul_f32_e32 v100, 0xbfb8aa3b, v100
	v_mul_f32_e32 v101, 0xbfb8aa3b, v101
	v_fma_f32 v110, -v108, v109, 1.0
	v_fmac_f32_e32 v109, v110, v109
	v_div_scale_f32 v110, vcc, 1.0, v103, 1.0
	v_mul_f32_e32 v111, v110, v109
	v_fma_f32 v112, -v108, v111, v110
	v_fmac_f32_e32 v111, v112, v109
	v_fma_f32 v108, -v108, v111, v110
	v_div_fmas_f32 v108, v108, v109, v111
	v_div_fixup_f32 v103, v108, v103, 1.0
	v_div_scale_f32 v108, s[16:17], v102, v102, 1.0
	v_rcp_f32_e32 v109, v108
	v_exp_f32_e32 v100, v100
	v_exp_f32_e32 v101, v101
	v_fma_f32 v110, -v108, v109, 1.0
	v_fmac_f32_e32 v109, v110, v109
	v_div_scale_f32 v110, vcc, 1.0, v102, 1.0
	v_mul_f32_e32 v111, v110, v109
	v_fma_f32 v112, -v108, v111, v110
	v_fmac_f32_e32 v111, v112, v109
	v_fma_f32 v108, -v108, v111, v110
	v_div_fmas_f32 v108, v108, v109, v111
	v_div_fixup_f32 v102, v108, v102, 1.0
	v_div_scale_f32 v108, s[16:17], v107, v107, 1.0
	v_rcp_f32_e32 v109, v108
	v_pk_add_f32 v[100:101], v[100:101], 1.0 op_sel_hi:[1,0]
	v_fma_f32 v110, -v108, v109, 1.0
	v_fmac_f32_e32 v109, v110, v109
	v_div_scale_f32 v110, vcc, 1.0, v107, 1.0
	v_mul_f32_e32 v111, v110, v109
	v_fma_f32 v112, -v108, v111, v110
	v_fmac_f32_e32 v111, v112, v109
	v_fma_f32 v108, -v108, v111, v110
	v_div_fmas_f32 v108, v108, v109, v111
	v_div_fixup_f32 v107, v108, v107, 1.0
	v_div_scale_f32 v108, s[16:17], v106, v106, 1.0
	v_rcp_f32_e32 v109, v108
	s_nop 0
	v_fma_f32 v110, -v108, v109, 1.0
	v_fmac_f32_e32 v109, v110, v109
	v_div_scale_f32 v110, vcc, 1.0, v106, 1.0
	v_mul_f32_e32 v111, v110, v109
	v_fma_f32 v112, -v108, v111, v110
	v_fmac_f32_e32 v111, v112, v109
	v_fma_f32 v108, -v108, v111, v110
	v_div_fmas_f32 v108, v108, v109, v111
	v_div_fixup_f32 v106, v108, v106, 1.0
	v_div_scale_f32 v108, s[16:17], v105, v105, 1.0
	v_rcp_f32_e32 v109, v108
	s_nop 0
	v_fma_f32 v110, -v108, v109, 1.0
	v_fmac_f32_e32 v109, v110, v109
	v_div_scale_f32 v110, vcc, 1.0, v105, 1.0
	v_mul_f32_e32 v111, v110, v109
	v_fma_f32 v112, -v108, v111, v110
	v_fmac_f32_e32 v111, v112, v109
	v_fma_f32 v108, -v108, v111, v110
	v_div_fmas_f32 v108, v108, v109, v111
	v_div_fixup_f32 v105, v108, v105, 1.0
	v_div_scale_f32 v108, s[16:17], v104, v104, 1.0
	v_rcp_f32_e32 v109, v108
	s_nop 0
	v_fma_f32 v110, -v108, v109, 1.0
	v_fmac_f32_e32 v109, v110, v109
	v_div_scale_f32 v110, vcc, 1.0, v104, 1.0
	v_mul_f32_e32 v111, v110, v109
	v_fma_f32 v112, -v108, v111, v110
	v_fmac_f32_e32 v111, v112, v109
	v_fma_f32 v108, -v108, v111, v110
	v_div_fmas_f32 v108, v108, v109, v111
	v_div_fixup_f32 v104, v108, v104, 1.0
	v_div_scale_f32 v108, s[16:17], v101, v101, 1.0
	v_rcp_f32_e32 v109, v108
	s_nop 0
	v_fma_f32 v110, -v108, v109, 1.0
	v_fmac_f32_e32 v109, v110, v109
	v_div_scale_f32 v110, vcc, 1.0, v101, 1.0
	v_mul_f32_e32 v111, v110, v109
	v_fma_f32 v112, -v108, v111, v110
	v_fmac_f32_e32 v111, v112, v109
	v_fma_f32 v108, -v108, v111, v110
	v_div_fmas_f32 v108, v108, v109, v111
	v_div_fixup_f32 v101, v108, v101, 1.0
	v_div_scale_f32 v108, s[16:17], v100, v100, 1.0
	v_rcp_f32_e32 v109, v108
	s_mov_b64 s[16:17], 0
	v_fma_f32 v110, -v108, v109, 1.0
	v_fmac_f32_e32 v109, v110, v109
	v_div_scale_f32 v110, vcc, 1.0, v100, 1.0
	v_mul_f32_e32 v111, v110, v109
	v_fma_f32 v112, -v108, v111, v110
	v_fmac_f32_e32 v111, v112, v109
	v_fma_f32 v108, -v108, v111, v110
	v_div_fmas_f32 v108, v108, v109, v111
	v_div_fixup_f32 v100, v108, v100, 1.0
	v_pk_mul_f32 v[110:111], s[18:19], v[100:101] op_sel_hi:[0,1]
	v_pk_mul_f32 v[108:109], s[18:19], v[104:105] op_sel_hi:[0,1]
	v_pk_mul_f32 v[104:105], s[18:19], v[106:107] op_sel_hi:[0,1]
	v_pk_mul_f32 v[100:101], s[18:19], v[102:103] op_sel_hi:[0,1]

.LBB0_1283:
	s_cmp_gt_i32 s19, 3
	s_mov_b64 s[16:17], -1
	s_cbranch_scc0 .LBB0_1285
	v_mov_b32_e32 v90, v190
	v_mov_b32_e32 v91, v191
	v_mov_b32_e32 v92, v192
	v_mov_b32_e32 v93, v193
	v_mov_b32_e32 v94, v186
	v_mov_b32_e32 v95, v187
	v_mov_b32_e32 v96, v188
	v_mov_b32_e32 v97, v189
	v_add_f32_e32 v90, v82, v90
	v_add_f32_e32 v94, v86, v94
	v_mul_f32_e32 v94, 0xbfb8aa3b, v94
	v_exp_f32_e32 v100, v94
	v_add_f32_e32 v94, v87, v95
	v_mul_f32_e32 v94, 0xbfb8aa3b, v94
	v_exp_f32_e32 v101, v94
	v_add_f32_e32 v94, v88, v96
	v_mul_f32_e32 v94, 0xbfb8aa3b, v94
	v_exp_f32_e32 v96, v94
	v_add_f32_e32 v94, v89, v97
	v_mul_f32_e32 v94, 0xbfb8aa3b, v94
	v_mul_f32_e32 v90, 0xbfb8aa3b, v90
	v_exp_f32_e32 v97, v94
	v_exp_f32_e32 v94, v90
	v_add_f32_e32 v90, v83, v91
	v_mul_f32_e32 v90, 0xbfb8aa3b, v90
	v_exp_f32_e32 v95, v90
	v_add_f32_e32 v90, v84, v92
	v_add_f32_e32 v91, v85, v93
	v_pk_add_f32 v[92:93], v[100:101], 1.0 op_sel_hi:[1,0]
	v_pk_add_f32 v[96:97], v[96:97], 1.0 op_sel_hi:[1,0]
	v_div_scale_f32 v100, s[16:17], v93, v93, 1.0
	v_rcp_f32_e32 v101, v100
	v_pk_add_f32 v[94:95], v[94:95], 1.0 op_sel_hi:[1,0]
	v_mul_f32_e32 v90, 0xbfb8aa3b, v90
	v_mul_f32_e32 v91, 0xbfb8aa3b, v91
	v_fma_f32 v102, -v100, v101, 1.0
	v_fmac_f32_e32 v101, v102, v101
	v_div_scale_f32 v102, vcc, 1.0, v93, 1.0
	v_mul_f32_e32 v103, v102, v101
	v_fma_f32 v104, -v100, v103, v102
	v_fmac_f32_e32 v103, v104, v101
	v_fma_f32 v100, -v100, v103, v102
	v_div_fmas_f32 v100, v100, v101, v103
	v_div_fixup_f32 v93, v100, v93, 1.0
	v_div_scale_f32 v100, s[16:17], v92, v92, 1.0
	v_rcp_f32_e32 v101, v100
	v_exp_f32_e32 v90, v90
	v_exp_f32_e32 v91, v91
	v_fma_f32 v102, -v100, v101, 1.0
	v_fmac_f32_e32 v101, v102, v101
	v_div_scale_f32 v102, vcc, 1.0, v92, 1.0
	v_mul_f32_e32 v103, v102, v101
	v_fma_f32 v104, -v100, v103, v102
	v_fmac_f32_e32 v103, v104, v101
	v_fma_f32 v100, -v100, v103, v102
	v_div_fmas_f32 v100, v100, v101, v103
	v_div_fixup_f32 v92, v100, v92, 1.0
	v_div_scale_f32 v100, s[16:17], v97, v97, 1.0
	v_rcp_f32_e32 v101, v100
	v_pk_add_f32 v[90:91], v[90:91], 1.0 op_sel_hi:[1,0]
	v_pk_mul_f32 v[92:93], s[18:19], v[92:93] op_sel_hi:[0,1]
	v_fma_f32 v102, -v100, v101, 1.0
	v_fmac_f32_e32 v101, v102, v101
	v_div_scale_f32 v102, vcc, 1.0, v97, 1.0
	v_mul_f32_e32 v103, v102, v101
	v_fma_f32 v104, -v100, v103, v102
	v_fmac_f32_e32 v103, v104, v101
	v_fma_f32 v100, -v100, v103, v102
	v_div_fmas_f32 v100, v100, v101, v103
	v_div_fixup_f32 v97, v100, v97, 1.0
	v_div_scale_f32 v100, s[16:17], v96, v96, 1.0
	v_rcp_f32_e32 v101, v100
	s_nop 0
	v_fma_f32 v102, -v100, v101, 1.0
	v_fmac_f32_e32 v101, v102, v101
	v_div_scale_f32 v102, vcc, 1.0, v96, 1.0
	v_mul_f32_e32 v103, v102, v101
	v_fma_f32 v104, -v100, v103, v102
	v_fmac_f32_e32 v103, v104, v101
	v_fma_f32 v100, -v100, v103, v102
	v_div_fmas_f32 v100, v100, v101, v103
	v_div_fixup_f32 v96, v100, v96, 1.0
	v_div_scale_f32 v100, s[16:17], v95, v95, 1.0
	v_rcp_f32_e32 v101, v100
	v_pk_mul_f32 v[96:97], s[18:19], v[96:97] op_sel_hi:[0,1]
	v_fma_f32 v102, -v100, v101, 1.0
	v_fmac_f32_e32 v101, v102, v101
	v_div_scale_f32 v102, vcc, 1.0, v95, 1.0
	v_mul_f32_e32 v103, v102, v101
	v_fma_f32 v104, -v100, v103, v102
	v_fmac_f32_e32 v103, v104, v101
	v_fma_f32 v100, -v100, v103, v102
	v_div_fmas_f32 v100, v100, v101, v103
	v_div_fixup_f32 v95, v100, v95, 1.0
	v_div_scale_f32 v100, s[16:17], v94, v94, 1.0
	v_rcp_f32_e32 v101, v100
	s_nop 0
	v_fma_f32 v102, -v100, v101, 1.0
	v_fmac_f32_e32 v101, v102, v101
	v_div_scale_f32 v102, vcc, 1.0, v94, 1.0
	v_mul_f32_e32 v103, v102, v101
	v_fma_f32 v104, -v100, v103, v102
	v_fmac_f32_e32 v103, v104, v101
	v_fma_f32 v100, -v100, v103, v102
	v_div_fmas_f32 v100, v100, v101, v103
	v_div_fixup_f32 v94, v100, v94, 1.0
	v_div_scale_f32 v100, s[16:17], v91, v91, 1.0
	v_rcp_f32_e32 v101, v100
	v_pk_mul_f32 v[94:95], s[18:19], v[94:95] op_sel_hi:[0,1]
	v_fma_f32 v102, -v100, v101, 1.0
	v_fmac_f32_e32 v101, v102, v101
	v_div_scale_f32 v102, vcc, 1.0, v91, 1.0
	v_mul_f32_e32 v103, v102, v101
	v_fma_f32 v104, -v100, v103, v102
	v_fmac_f32_e32 v103, v104, v101
	v_fma_f32 v100, -v100, v103, v102
	v_div_fmas_f32 v100, v100, v101, v103
	v_div_fixup_f32 v91, v100, v91, 1.0
	v_div_scale_f32 v100, s[16:17], v90, v90, 1.0
	v_rcp_f32_e32 v101, v100
	s_nop 0
	v_fma_f32 v102, -v100, v101, 1.0
	v_fmac_f32_e32 v101, v102, v101
	v_div_scale_f32 v102, vcc, 1.0, v90, 1.0
	v_mul_f32_e32 v103, v102, v101
	v_fma_f32 v104, -v100, v103, v102
	v_fmac_f32_e32 v103, v104, v101
	v_fma_f32 v100, -v100, v103, v102
	v_div_fmas_f32 v100, v100, v101, v103
	v_div_fixup_f32 v90, v100, v90, 1.0
	v_pk_mul_f32 v[90:91], s[18:19], v[90:91] op_sel_hi:[0,1]
	s_cbranch_execnz .LBB0_1289
	s_branch .LBB0_1286

.LBB0_1295:
	s_cmp_lt_i32 s5, 3
	s_mov_b64 s[16:17], -1
	s_cbranch_scc1 .LBB0_1301
	s_cmp_gt_i32 s5, 3
	s_cbranch_scc0 .LBB0_1298
	v_mov_b32_e32 v84, v182
	v_mov_b32_e32 v85, v183
	v_mov_b32_e32 v86, v184
	v_mov_b32_e32 v87, v185
	v_mov_b32_e32 v88, v178
	v_mov_b32_e32 v89, v179
	v_mov_b32_e32 v90, v180
	v_mov_b32_e32 v91, v181
	v_add_f32_e32 v84, v74, v84
	v_add_f32_e32 v88, v78, v88
	v_mul_f32_e32 v88, 0xbfb8aa3b, v88
	v_exp_f32_e32 v92, v88
	v_add_f32_e32 v88, v79, v89
	v_mul_f32_e32 v88, 0xbfb8aa3b, v88
	v_exp_f32_e32 v93, v88
	v_add_f32_e32 v88, v80, v90
	v_mul_f32_e32 v88, 0xbfb8aa3b, v88
	v_exp_f32_e32 v90, v88
	v_add_f32_e32 v88, v81, v91
	v_mul_f32_e32 v88, 0xbfb8aa3b, v88
	v_mul_f32_e32 v84, 0xbfb8aa3b, v84
	v_exp_f32_e32 v91, v88
	v_exp_f32_e32 v88, v84
	v_add_f32_e32 v84, v75, v85
	v_mul_f32_e32 v84, 0xbfb8aa3b, v84
	v_exp_f32_e32 v89, v84
	v_add_f32_e32 v84, v76, v86
	v_add_f32_e32 v85, v77, v87
	v_pk_add_f32 v[86:87], v[92:93], 1.0 op_sel_hi:[1,0]
	v_pk_add_f32 v[90:91], v[90:91], 1.0 op_sel_hi:[1,0]
	v_div_scale_f32 v92, s[16:17], v87, v87, 1.0
	v_rcp_f32_e32 v93, v92
	v_pk_add_f32 v[88:89], v[88:89], 1.0 op_sel_hi:[1,0]
	v_mul_f32_e32 v84, 0xbfb8aa3b, v84
	v_mul_f32_e32 v85, 0xbfb8aa3b, v85
	v_fma_f32 v94, -v92, v93, 1.0
	v_fmac_f32_e32 v93, v94, v93
	v_div_scale_f32 v94, vcc, 1.0, v87, 1.0
	v_mul_f32_e32 v95, v94, v93
	v_fma_f32 v96, -v92, v95, v94
	v_fmac_f32_e32 v95, v96, v93
	v_fma_f32 v92, -v92, v95, v94
	v_div_fmas_f32 v92, v92, v93, v95
	v_div_fixup_f32 v87, v92, v87, 1.0
	v_div_scale_f32 v92, s[16:17], v86, v86, 1.0
	v_rcp_f32_e32 v93, v92
	v_exp_f32_e32 v84, v84
	v_exp_f32_e32 v85, v85
	v_fma_f32 v94, -v92, v93, 1.0
	v_fmac_f32_e32 v93, v94, v93
	v_div_scale_f32 v94, vcc, 1.0, v86, 1.0
	v_mul_f32_e32 v95, v94, v93
	v_fma_f32 v96, -v92, v95, v94
	v_fmac_f32_e32 v95, v96, v93
	v_fma_f32 v92, -v92, v95, v94
	v_div_fmas_f32 v92, v92, v93, v95
	v_div_fixup_f32 v86, v92, v86, 1.0
	v_div_scale_f32 v92, s[16:17], v91, v91, 1.0
	v_rcp_f32_e32 v93, v92
	v_pk_add_f32 v[84:85], v[84:85], 1.0 op_sel_hi:[1,0]
	v_fma_f32 v94, -v92, v93, 1.0
	v_fmac_f32_e32 v93, v94, v93
	v_div_scale_f32 v94, vcc, 1.0, v91, 1.0
	v_mul_f32_e32 v95, v94, v93
	v_fma_f32 v96, -v92, v95, v94
	v_fmac_f32_e32 v95, v96, v93
	v_fma_f32 v92, -v92, v95, v94
	v_div_fmas_f32 v92, v92, v93, v95
	v_div_fixup_f32 v91, v92, v91, 1.0
	v_div_scale_f32 v92, s[16:17], v90, v90, 1.0
	v_rcp_f32_e32 v93, v92
	s_nop 0
	v_fma_f32 v94, -v92, v93, 1.0
	v_fmac_f32_e32 v93, v94, v93
	v_div_scale_f32 v94, vcc, 1.0, v90, 1.0
	v_mul_f32_e32 v95, v94, v93
	v_fma_f32 v96, -v92, v95, v94
	v_fmac_f32_e32 v95, v96, v93
	v_fma_f32 v92, -v92, v95, v94
	v_div_fmas_f32 v92, v92, v93, v95
	v_div_fixup_f32 v90, v92, v90, 1.0
	v_div_scale_f32 v92, s[16:17], v89, v89, 1.0
	v_rcp_f32_e32 v93, v92
	s_nop 0
	v_fma_f32 v94, -v92, v93, 1.0
	v_fmac_f32_e32 v93, v94, v93
	v_div_scale_f32 v94, vcc, 1.0, v89, 1.0
	v_mul_f32_e32 v95, v94, v93
	v_fma_f32 v96, -v92, v95, v94
	v_fmac_f32_e32 v95, v96, v93
	v_fma_f32 v92, -v92, v95, v94
	v_div_fmas_f32 v92, v92, v93, v95
	v_div_fixup_f32 v89, v92, v89, 1.0
	v_div_scale_f32 v92, s[16:17], v88, v88, 1.0
	v_rcp_f32_e32 v93, v92
	s_nop 0
	v_fma_f32 v94, -v92, v93, 1.0
	v_fmac_f32_e32 v93, v94, v93
	v_div_scale_f32 v94, vcc, 1.0, v88, 1.0
	v_mul_f32_e32 v95, v94, v93
	v_fma_f32 v96, -v92, v95, v94
	v_fmac_f32_e32 v95, v96, v93
	v_fma_f32 v92, -v92, v95, v94
	v_div_fmas_f32 v92, v92, v93, v95
	v_div_fixup_f32 v88, v92, v88, 1.0
	v_div_scale_f32 v92, s[16:17], v85, v85, 1.0
	v_rcp_f32_e32 v93, v92
	s_nop 0
	v_fma_f32 v94, -v92, v93, 1.0
	v_fmac_f32_e32 v93, v94, v93
	v_div_scale_f32 v94, vcc, 1.0, v85, 1.0
	v_mul_f32_e32 v95, v94, v93
	v_fma_f32 v96, -v92, v95, v94
	v_fmac_f32_e32 v95, v96, v93
	v_fma_f32 v92, -v92, v95, v94
	v_div_fmas_f32 v92, v92, v93, v95
	v_div_fixup_f32 v85, v92, v85, 1.0
	v_div_scale_f32 v92, s[16:17], v84, v84, 1.0
	v_rcp_f32_e32 v93, v92
	s_mov_b64 s[16:17], 0
	v_fma_f32 v94, -v92, v93, 1.0
	v_fmac_f32_e32 v93, v94, v93
	v_div_scale_f32 v94, vcc, 1.0, v84, 1.0
	v_mul_f32_e32 v95, v94, v93
	v_fma_f32 v96, -v92, v95, v94
	v_fmac_f32_e32 v95, v96, v93
	v_fma_f32 v92, -v92, v95, v94
	v_div_fmas_f32 v92, v92, v93, v95
	v_div_fixup_f32 v84, v92, v84, 1.0
	v_pk_mul_f32 v[94:95], s[18:19], v[84:85] op_sel_hi:[0,1]
	v_pk_mul_f32 v[92:93], s[18:19], v[88:89] op_sel_hi:[0,1]
	v_pk_mul_f32 v[88:89], s[18:19], v[90:91] op_sel_hi:[0,1]
	v_pk_mul_f32 v[84:85], s[18:19], v[86:87] op_sel_hi:[0,1]

.LBB0_1311:
	s_cmp_gt_i32 s19, 3
	s_mov_b64 s[16:17], -1
	s_cbranch_scc0 .LBB0_1313
	v_mov_b32_e32 v74, v190
	v_mov_b32_e32 v75, v191
	v_mov_b32_e32 v76, v192
	v_mov_b32_e32 v77, v193
	v_mov_b32_e32 v78, v186
	v_mov_b32_e32 v79, v187
	v_mov_b32_e32 v80, v188
	v_mov_b32_e32 v81, v189
	v_add_f32_e32 v74, v66, v74
	v_add_f32_e32 v78, v70, v78
	v_mul_f32_e32 v78, 0xbfb8aa3b, v78
	v_exp_f32_e32 v84, v78
	v_add_f32_e32 v78, v71, v79
	v_mul_f32_e32 v78, 0xbfb8aa3b, v78
	v_exp_f32_e32 v85, v78
	v_add_f32_e32 v78, v72, v80
	v_mul_f32_e32 v78, 0xbfb8aa3b, v78
	v_exp_f32_e32 v80, v78
	v_add_f32_e32 v78, v73, v81
	v_mul_f32_e32 v78, 0xbfb8aa3b, v78
	v_mul_f32_e32 v74, 0xbfb8aa3b, v74
	v_exp_f32_e32 v81, v78
	v_exp_f32_e32 v78, v74
	v_add_f32_e32 v74, v67, v75
	v_mul_f32_e32 v74, 0xbfb8aa3b, v74
	v_exp_f32_e32 v79, v74
	v_add_f32_e32 v74, v68, v76
	v_add_f32_e32 v75, v69, v77
	v_pk_add_f32 v[76:77], v[84:85], 1.0 op_sel_hi:[1,0]
	v_pk_add_f32 v[80:81], v[80:81], 1.0 op_sel_hi:[1,0]
	v_div_scale_f32 v84, s[16:17], v77, v77, 1.0
	v_rcp_f32_e32 v85, v84
	v_pk_add_f32 v[78:79], v[78:79], 1.0 op_sel_hi:[1,0]
	v_mul_f32_e32 v74, 0xbfb8aa3b, v74
	v_mul_f32_e32 v75, 0xbfb8aa3b, v75
	v_fma_f32 v86, -v84, v85, 1.0
	v_fmac_f32_e32 v85, v86, v85
	v_div_scale_f32 v86, vcc, 1.0, v77, 1.0
	v_mul_f32_e32 v87, v86, v85
	v_fma_f32 v88, -v84, v87, v86
	v_fmac_f32_e32 v87, v88, v85
	v_fma_f32 v84, -v84, v87, v86
	v_div_fmas_f32 v84, v84, v85, v87
	v_div_fixup_f32 v77, v84, v77, 1.0
	v_div_scale_f32 v84, s[16:17], v76, v76, 1.0
	v_rcp_f32_e32 v85, v84
	v_exp_f32_e32 v74, v74
	v_exp_f32_e32 v75, v75
	v_fma_f32 v86, -v84, v85, 1.0
	v_fmac_f32_e32 v85, v86, v85
	v_div_scale_f32 v86, vcc, 1.0, v76, 1.0
	v_mul_f32_e32 v87, v86, v85
	v_fma_f32 v88, -v84, v87, v86
	v_fmac_f32_e32 v87, v88, v85
	v_fma_f32 v84, -v84, v87, v86
	v_div_fmas_f32 v84, v84, v85, v87
	v_div_fixup_f32 v76, v84, v76, 1.0
	v_div_scale_f32 v84, s[16:17], v81, v81, 1.0
	v_rcp_f32_e32 v85, v84
	v_pk_add_f32 v[74:75], v[74:75], 1.0 op_sel_hi:[1,0]
	v_pk_mul_f32 v[76:77], s[18:19], v[76:77] op_sel_hi:[0,1]
	v_fma_f32 v86, -v84, v85, 1.0
	v_fmac_f32_e32 v85, v86, v85
	v_div_scale_f32 v86, vcc, 1.0, v81, 1.0
	v_mul_f32_e32 v87, v86, v85
	v_fma_f32 v88, -v84, v87, v86
	v_fmac_f32_e32 v87, v88, v85
	v_fma_f32 v84, -v84, v87, v86
	v_div_fmas_f32 v84, v84, v85, v87
	v_div_fixup_f32 v81, v84, v81, 1.0
	v_div_scale_f32 v84, s[16:17], v80, v80, 1.0
	v_rcp_f32_e32 v85, v84
	s_nop 0
	v_fma_f32 v86, -v84, v85, 1.0
	v_fmac_f32_e32 v85, v86, v85
	v_div_scale_f32 v86, vcc, 1.0, v80, 1.0
	v_mul_f32_e32 v87, v86, v85
	v_fma_f32 v88, -v84, v87, v86
	v_fmac_f32_e32 v87, v88, v85
	v_fma_f32 v84, -v84, v87, v86
	v_div_fmas_f32 v84, v84, v85, v87
	v_div_fixup_f32 v80, v84, v80, 1.0
	v_div_scale_f32 v84, s[16:17], v79, v79, 1.0
	v_rcp_f32_e32 v85, v84
	v_pk_mul_f32 v[80:81], s[18:19], v[80:81] op_sel_hi:[0,1]
	v_fma_f32 v86, -v84, v85, 1.0
	v_fmac_f32_e32 v85, v86, v85
	v_div_scale_f32 v86, vcc, 1.0, v79, 1.0
	v_mul_f32_e32 v87, v86, v85
	v_fma_f32 v88, -v84, v87, v86
	v_fmac_f32_e32 v87, v88, v85
	v_fma_f32 v84, -v84, v87, v86
	v_div_fmas_f32 v84, v84, v85, v87
	v_div_fixup_f32 v79, v84, v79, 1.0
	v_div_scale_f32 v84, s[16:17], v78, v78, 1.0
	v_rcp_f32_e32 v85, v84
	s_nop 0
	v_fma_f32 v86, -v84, v85, 1.0
	v_fmac_f32_e32 v85, v86, v85
	v_div_scale_f32 v86, vcc, 1.0, v78, 1.0
	v_mul_f32_e32 v87, v86, v85
	v_fma_f32 v88, -v84, v87, v86
	v_fmac_f32_e32 v87, v88, v85
	v_fma_f32 v84, -v84, v87, v86
	v_div_fmas_f32 v84, v84, v85, v87
	v_div_fixup_f32 v78, v84, v78, 1.0
	v_div_scale_f32 v84, s[16:17], v75, v75, 1.0
	v_rcp_f32_e32 v85, v84
	v_pk_mul_f32 v[78:79], s[18:19], v[78:79] op_sel_hi:[0,1]
	v_fma_f32 v86, -v84, v85, 1.0
	v_fmac_f32_e32 v85, v86, v85
	v_div_scale_f32 v86, vcc, 1.0, v75, 1.0
	v_mul_f32_e32 v87, v86, v85
	v_fma_f32 v88, -v84, v87, v86
	v_fmac_f32_e32 v87, v88, v85
	v_fma_f32 v84, -v84, v87, v86
	v_div_fmas_f32 v84, v84, v85, v87
	v_div_fixup_f32 v75, v84, v75, 1.0
	v_div_scale_f32 v84, s[16:17], v74, v74, 1.0
	v_rcp_f32_e32 v85, v84
	s_nop 0
	v_fma_f32 v86, -v84, v85, 1.0
	v_fmac_f32_e32 v85, v86, v85
	v_div_scale_f32 v86, vcc, 1.0, v74, 1.0
	v_mul_f32_e32 v87, v86, v85
	v_fma_f32 v88, -v84, v87, v86
	v_fmac_f32_e32 v87, v88, v85
	v_fma_f32 v84, -v84, v87, v86
	v_div_fmas_f32 v84, v84, v85, v87
	v_div_fixup_f32 v74, v84, v74, 1.0
	v_pk_mul_f32 v[74:75], s[18:19], v[74:75] op_sel_hi:[0,1]
	s_cbranch_execnz .LBB0_1317
	s_branch .LBB0_1314

.LBB0_1323:
	s_cmp_lt_i32 s5, 3
	s_mov_b64 s[16:17], -1
	s_cbranch_scc1 .LBB0_1329
	s_cmp_gt_i32 s5, 3
	s_cbranch_scc0 .LBB0_1326
	v_mov_b32_e32 v68, v182
	v_mov_b32_e32 v69, v183
	v_mov_b32_e32 v70, v184
	v_mov_b32_e32 v71, v185
	v_mov_b32_e32 v72, v178
	v_mov_b32_e32 v73, v179
	v_mov_b32_e32 v74, v180
	v_mov_b32_e32 v75, v181
	v_add_f32_e32 v68, v58, v68
	v_add_f32_e32 v72, v62, v72
	v_mul_f32_e32 v72, 0xbfb8aa3b, v72
	v_exp_f32_e32 v76, v72
	v_add_f32_e32 v72, v63, v73
	v_mul_f32_e32 v72, 0xbfb8aa3b, v72
	v_exp_f32_e32 v77, v72
	v_add_f32_e32 v72, v64, v74
	v_mul_f32_e32 v72, 0xbfb8aa3b, v72
	v_exp_f32_e32 v74, v72
	v_add_f32_e32 v72, v65, v75
	v_mul_f32_e32 v72, 0xbfb8aa3b, v72
	v_mul_f32_e32 v68, 0xbfb8aa3b, v68
	v_exp_f32_e32 v75, v72
	v_exp_f32_e32 v72, v68
	v_add_f32_e32 v68, v59, v69
	v_mul_f32_e32 v68, 0xbfb8aa3b, v68
	v_exp_f32_e32 v73, v68
	v_add_f32_e32 v68, v60, v70
	v_add_f32_e32 v69, v61, v71
	v_pk_add_f32 v[70:71], v[76:77], 1.0 op_sel_hi:[1,0]
	v_pk_add_f32 v[74:75], v[74:75], 1.0 op_sel_hi:[1,0]
	v_div_scale_f32 v76, s[16:17], v71, v71, 1.0
	v_rcp_f32_e32 v77, v76
	v_pk_add_f32 v[72:73], v[72:73], 1.0 op_sel_hi:[1,0]
	v_mul_f32_e32 v68, 0xbfb8aa3b, v68
	v_mul_f32_e32 v69, 0xbfb8aa3b, v69
	v_fma_f32 v78, -v76, v77, 1.0
	v_fmac_f32_e32 v77, v78, v77
	v_div_scale_f32 v78, vcc, 1.0, v71, 1.0
	v_mul_f32_e32 v79, v78, v77
	v_fma_f32 v80, -v76, v79, v78
	v_fmac_f32_e32 v79, v80, v77
	v_fma_f32 v76, -v76, v79, v78
	v_div_fmas_f32 v76, v76, v77, v79
	v_div_fixup_f32 v71, v76, v71, 1.0
	v_div_scale_f32 v76, s[16:17], v70, v70, 1.0
	v_rcp_f32_e32 v77, v76
	v_exp_f32_e32 v68, v68
	v_exp_f32_e32 v69, v69
	v_fma_f32 v78, -v76, v77, 1.0
	v_fmac_f32_e32 v77, v78, v77
	v_div_scale_f32 v78, vcc, 1.0, v70, 1.0
	v_mul_f32_e32 v79, v78, v77
	v_fma_f32 v80, -v76, v79, v78
	v_fmac_f32_e32 v79, v80, v77
	v_fma_f32 v76, -v76, v79, v78
	v_div_fmas_f32 v76, v76, v77, v79
	v_div_fixup_f32 v70, v76, v70, 1.0
	v_div_scale_f32 v76, s[16:17], v75, v75, 1.0
	v_rcp_f32_e32 v77, v76
	v_pk_add_f32 v[68:69], v[68:69], 1.0 op_sel_hi:[1,0]
	v_fma_f32 v78, -v76, v77, 1.0
	v_fmac_f32_e32 v77, v78, v77
	v_div_scale_f32 v78, vcc, 1.0, v75, 1.0
	v_mul_f32_e32 v79, v78, v77
	v_fma_f32 v80, -v76, v79, v78
	v_fmac_f32_e32 v79, v80, v77
	v_fma_f32 v76, -v76, v79, v78
	v_div_fmas_f32 v76, v76, v77, v79
	v_div_fixup_f32 v75, v76, v75, 1.0
	v_div_scale_f32 v76, s[16:17], v74, v74, 1.0
	v_rcp_f32_e32 v77, v76
	s_nop 0
	v_fma_f32 v78, -v76, v77, 1.0
	v_fmac_f32_e32 v77, v78, v77
	v_div_scale_f32 v78, vcc, 1.0, v74, 1.0
	v_mul_f32_e32 v79, v78, v77
	v_fma_f32 v80, -v76, v79, v78
	v_fmac_f32_e32 v79, v80, v77
	v_fma_f32 v76, -v76, v79, v78
	v_div_fmas_f32 v76, v76, v77, v79
	v_div_fixup_f32 v74, v76, v74, 1.0
	v_div_scale_f32 v76, s[16:17], v73, v73, 1.0
	v_rcp_f32_e32 v77, v76
	s_nop 0
	v_fma_f32 v78, -v76, v77, 1.0
	v_fmac_f32_e32 v77, v78, v77
	v_div_scale_f32 v78, vcc, 1.0, v73, 1.0
	v_mul_f32_e32 v79, v78, v77
	v_fma_f32 v80, -v76, v79, v78
	v_fmac_f32_e32 v79, v80, v77
	v_fma_f32 v76, -v76, v79, v78
	v_div_fmas_f32 v76, v76, v77, v79
	v_div_fixup_f32 v73, v76, v73, 1.0
	v_div_scale_f32 v76, s[16:17], v72, v72, 1.0
	v_rcp_f32_e32 v77, v76
	s_nop 0
	v_fma_f32 v78, -v76, v77, 1.0
	v_fmac_f32_e32 v77, v78, v77
	v_div_scale_f32 v78, vcc, 1.0, v72, 1.0
	v_mul_f32_e32 v79, v78, v77
	v_fma_f32 v80, -v76, v79, v78
	v_fmac_f32_e32 v79, v80, v77
	v_fma_f32 v76, -v76, v79, v78
	v_div_fmas_f32 v76, v76, v77, v79
	v_div_fixup_f32 v72, v76, v72, 1.0
	v_div_scale_f32 v76, s[16:17], v69, v69, 1.0
	v_rcp_f32_e32 v77, v76
	s_nop 0
	v_fma_f32 v78, -v76, v77, 1.0
	v_fmac_f32_e32 v77, v78, v77
	v_div_scale_f32 v78, vcc, 1.0, v69, 1.0
	v_mul_f32_e32 v79, v78, v77
	v_fma_f32 v80, -v76, v79, v78
	v_fmac_f32_e32 v79, v80, v77
	v_fma_f32 v76, -v76, v79, v78
	v_div_fmas_f32 v76, v76, v77, v79
	v_div_fixup_f32 v69, v76, v69, 1.0
	v_div_scale_f32 v76, s[16:17], v68, v68, 1.0
	v_rcp_f32_e32 v77, v76
	s_mov_b64 s[16:17], 0
	v_fma_f32 v78, -v76, v77, 1.0
	v_fmac_f32_e32 v77, v78, v77
	v_div_scale_f32 v78, vcc, 1.0, v68, 1.0
	v_mul_f32_e32 v79, v78, v77
	v_fma_f32 v80, -v76, v79, v78
	v_fmac_f32_e32 v79, v80, v77
	v_fma_f32 v76, -v76, v79, v78
	v_div_fmas_f32 v76, v76, v77, v79
	v_div_fixup_f32 v68, v76, v68, 1.0
	v_pk_mul_f32 v[78:79], s[18:19], v[68:69] op_sel_hi:[0,1]
	v_pk_mul_f32 v[76:77], s[18:19], v[72:73] op_sel_hi:[0,1]
	v_pk_mul_f32 v[72:73], s[18:19], v[74:75] op_sel_hi:[0,1]
	v_pk_mul_f32 v[68:69], s[18:19], v[70:71] op_sel_hi:[0,1]

.LBB0_1339:
	s_cmp_gt_i32 s19, 3
	s_mov_b64 s[16:17], -1
	s_cbranch_scc0 .LBB0_1341
	v_mov_b32_e32 v58, v190
	v_mov_b32_e32 v59, v191
	v_mov_b32_e32 v60, v192
	v_mov_b32_e32 v61, v193
	v_mov_b32_e32 v62, v186
	v_mov_b32_e32 v63, v187
	v_mov_b32_e32 v64, v188
	v_mov_b32_e32 v65, v189
	v_add_f32_e32 v58, v50, v58
	v_add_f32_e32 v62, v54, v62
	v_mul_f32_e32 v62, 0xbfb8aa3b, v62
	v_exp_f32_e32 v68, v62
	v_add_f32_e32 v62, v55, v63
	v_mul_f32_e32 v62, 0xbfb8aa3b, v62
	v_exp_f32_e32 v69, v62
	v_add_f32_e32 v62, v56, v64
	v_mul_f32_e32 v62, 0xbfb8aa3b, v62
	v_exp_f32_e32 v64, v62
	v_add_f32_e32 v62, v57, v65
	v_mul_f32_e32 v62, 0xbfb8aa3b, v62
	v_mul_f32_e32 v58, 0xbfb8aa3b, v58
	v_exp_f32_e32 v65, v62
	v_exp_f32_e32 v62, v58
	v_add_f32_e32 v58, v51, v59
	v_mul_f32_e32 v58, 0xbfb8aa3b, v58
	v_exp_f32_e32 v63, v58
	v_add_f32_e32 v58, v52, v60
	v_add_f32_e32 v59, v53, v61
	v_pk_add_f32 v[60:61], v[68:69], 1.0 op_sel_hi:[1,0]
	v_pk_add_f32 v[64:65], v[64:65], 1.0 op_sel_hi:[1,0]
	v_div_scale_f32 v68, s[16:17], v61, v61, 1.0
	v_rcp_f32_e32 v69, v68
	v_pk_add_f32 v[62:63], v[62:63], 1.0 op_sel_hi:[1,0]
	v_mul_f32_e32 v58, 0xbfb8aa3b, v58
	v_mul_f32_e32 v59, 0xbfb8aa3b, v59
	v_fma_f32 v70, -v68, v69, 1.0
	v_fmac_f32_e32 v69, v70, v69
	v_div_scale_f32 v70, vcc, 1.0, v61, 1.0
	v_mul_f32_e32 v71, v70, v69
	v_fma_f32 v72, -v68, v71, v70
	v_fmac_f32_e32 v71, v72, v69
	v_fma_f32 v68, -v68, v71, v70
	v_div_fmas_f32 v68, v68, v69, v71
	v_div_fixup_f32 v61, v68, v61, 1.0
	v_div_scale_f32 v68, s[16:17], v60, v60, 1.0
	v_rcp_f32_e32 v69, v68
	v_exp_f32_e32 v58, v58
	v_exp_f32_e32 v59, v59
	v_fma_f32 v70, -v68, v69, 1.0
	v_fmac_f32_e32 v69, v70, v69
	v_div_scale_f32 v70, vcc, 1.0, v60, 1.0
	v_mul_f32_e32 v71, v70, v69
	v_fma_f32 v72, -v68, v71, v70
	v_fmac_f32_e32 v71, v72, v69
	v_fma_f32 v68, -v68, v71, v70
	v_div_fmas_f32 v68, v68, v69, v71
	v_div_fixup_f32 v60, v68, v60, 1.0
	v_div_scale_f32 v68, s[16:17], v65, v65, 1.0
	v_rcp_f32_e32 v69, v68
	v_pk_add_f32 v[58:59], v[58:59], 1.0 op_sel_hi:[1,0]
	v_pk_mul_f32 v[60:61], s[18:19], v[60:61] op_sel_hi:[0,1]
	v_fma_f32 v70, -v68, v69, 1.0
	v_fmac_f32_e32 v69, v70, v69
	v_div_scale_f32 v70, vcc, 1.0, v65, 1.0
	v_mul_f32_e32 v71, v70, v69
	v_fma_f32 v72, -v68, v71, v70
	v_fmac_f32_e32 v71, v72, v69
	v_fma_f32 v68, -v68, v71, v70
	v_div_fmas_f32 v68, v68, v69, v71
	v_div_fixup_f32 v65, v68, v65, 1.0
	v_div_scale_f32 v68, s[16:17], v64, v64, 1.0
	v_rcp_f32_e32 v69, v68
	s_nop 0
	v_fma_f32 v70, -v68, v69, 1.0
	v_fmac_f32_e32 v69, v70, v69
	v_div_scale_f32 v70, vcc, 1.0, v64, 1.0
	v_mul_f32_e32 v71, v70, v69
	v_fma_f32 v72, -v68, v71, v70
	v_fmac_f32_e32 v71, v72, v69
	v_fma_f32 v68, -v68, v71, v70
	v_div_fmas_f32 v68, v68, v69, v71
	v_div_fixup_f32 v64, v68, v64, 1.0
	v_div_scale_f32 v68, s[16:17], v63, v63, 1.0
	v_rcp_f32_e32 v69, v68
	v_pk_mul_f32 v[64:65], s[18:19], v[64:65] op_sel_hi:[0,1]
	v_fma_f32 v70, -v68, v69, 1.0
	v_fmac_f32_e32 v69, v70, v69
	v_div_scale_f32 v70, vcc, 1.0, v63, 1.0
	v_mul_f32_e32 v71, v70, v69
	v_fma_f32 v72, -v68, v71, v70
	v_fmac_f32_e32 v71, v72, v69
	v_fma_f32 v68, -v68, v71, v70
	v_div_fmas_f32 v68, v68, v69, v71
	v_div_fixup_f32 v63, v68, v63, 1.0
	v_div_scale_f32 v68, s[16:17], v62, v62, 1.0
	v_rcp_f32_e32 v69, v68
	s_nop 0
	v_fma_f32 v70, -v68, v69, 1.0
	v_fmac_f32_e32 v69, v70, v69
	v_div_scale_f32 v70, vcc, 1.0, v62, 1.0
	v_mul_f32_e32 v71, v70, v69
	v_fma_f32 v72, -v68, v71, v70
	v_fmac_f32_e32 v71, v72, v69
	v_fma_f32 v68, -v68, v71, v70
	v_div_fmas_f32 v68, v68, v69, v71
	v_div_fixup_f32 v62, v68, v62, 1.0
	v_div_scale_f32 v68, s[16:17], v59, v59, 1.0
	v_rcp_f32_e32 v69, v68
	v_pk_mul_f32 v[62:63], s[18:19], v[62:63] op_sel_hi:[0,1]
	v_fma_f32 v70, -v68, v69, 1.0
	v_fmac_f32_e32 v69, v70, v69
	v_div_scale_f32 v70, vcc, 1.0, v59, 1.0
	v_mul_f32_e32 v71, v70, v69
	v_fma_f32 v72, -v68, v71, v70
	v_fmac_f32_e32 v71, v72, v69
	v_fma_f32 v68, -v68, v71, v70
	v_div_fmas_f32 v68, v68, v69, v71
	v_div_fixup_f32 v59, v68, v59, 1.0
	v_div_scale_f32 v68, s[16:17], v58, v58, 1.0
	v_rcp_f32_e32 v69, v68
	s_nop 0
	v_fma_f32 v70, -v68, v69, 1.0
	v_fmac_f32_e32 v69, v70, v69
	v_div_scale_f32 v70, vcc, 1.0, v58, 1.0
	v_mul_f32_e32 v71, v70, v69
	v_fma_f32 v72, -v68, v71, v70
	v_fmac_f32_e32 v71, v72, v69
	v_fma_f32 v68, -v68, v71, v70
	v_div_fmas_f32 v68, v68, v69, v71
	v_div_fixup_f32 v58, v68, v58, 1.0
	v_pk_mul_f32 v[58:59], s[18:19], v[58:59] op_sel_hi:[0,1]
	s_cbranch_execnz .LBB0_1345
	s_branch .LBB0_1342

.LBB0_1351:
	s_cmp_lt_i32 s5, 3
	s_mov_b64 s[16:17], -1
	s_cbranch_scc1 .LBB0_1357
	s_cmp_gt_i32 s5, 3
	s_cbranch_scc0 .LBB0_1354
	v_mov_b32_e32 v52, v182
	v_mov_b32_e32 v53, v183
	v_mov_b32_e32 v54, v184
	v_mov_b32_e32 v55, v185
	v_mov_b32_e32 v56, v178
	v_mov_b32_e32 v57, v179
	v_mov_b32_e32 v58, v180
	v_mov_b32_e32 v59, v181
	v_add_f32_e32 v52, v42, v52
	v_add_f32_e32 v56, v46, v56
	v_mul_f32_e32 v56, 0xbfb8aa3b, v56
	v_exp_f32_e32 v60, v56
	v_add_f32_e32 v56, v47, v57
	v_mul_f32_e32 v56, 0xbfb8aa3b, v56
	v_exp_f32_e32 v61, v56
	v_add_f32_e32 v56, v48, v58
	v_mul_f32_e32 v56, 0xbfb8aa3b, v56
	v_exp_f32_e32 v58, v56
	v_add_f32_e32 v56, v49, v59
	v_mul_f32_e32 v56, 0xbfb8aa3b, v56
	v_mul_f32_e32 v52, 0xbfb8aa3b, v52
	v_exp_f32_e32 v59, v56
	v_exp_f32_e32 v56, v52
	v_add_f32_e32 v52, v43, v53
	v_mul_f32_e32 v52, 0xbfb8aa3b, v52
	v_exp_f32_e32 v57, v52
	v_add_f32_e32 v52, v44, v54
	v_add_f32_e32 v53, v45, v55
	v_pk_add_f32 v[54:55], v[60:61], 1.0 op_sel_hi:[1,0]
	v_pk_add_f32 v[58:59], v[58:59], 1.0 op_sel_hi:[1,0]
	v_div_scale_f32 v60, s[16:17], v55, v55, 1.0
	v_rcp_f32_e32 v61, v60
	v_pk_add_f32 v[56:57], v[56:57], 1.0 op_sel_hi:[1,0]
	v_mul_f32_e32 v52, 0xbfb8aa3b, v52
	v_mul_f32_e32 v53, 0xbfb8aa3b, v53
	v_fma_f32 v62, -v60, v61, 1.0
	v_fmac_f32_e32 v61, v62, v61
	v_div_scale_f32 v62, vcc, 1.0, v55, 1.0
	v_mul_f32_e32 v63, v62, v61
	v_fma_f32 v64, -v60, v63, v62
	v_fmac_f32_e32 v63, v64, v61
	v_fma_f32 v60, -v60, v63, v62
	v_div_fmas_f32 v60, v60, v61, v63
	v_div_fixup_f32 v55, v60, v55, 1.0
	v_div_scale_f32 v60, s[16:17], v54, v54, 1.0
	v_rcp_f32_e32 v61, v60
	v_exp_f32_e32 v52, v52
	v_exp_f32_e32 v53, v53
	v_fma_f32 v62, -v60, v61, 1.0
	v_fmac_f32_e32 v61, v62, v61
	v_div_scale_f32 v62, vcc, 1.0, v54, 1.0
	v_mul_f32_e32 v63, v62, v61
	v_fma_f32 v64, -v60, v63, v62
	v_fmac_f32_e32 v63, v64, v61
	v_fma_f32 v60, -v60, v63, v62
	v_div_fmas_f32 v60, v60, v61, v63
	v_div_fixup_f32 v54, v60, v54, 1.0
	v_div_scale_f32 v60, s[16:17], v59, v59, 1.0
	v_rcp_f32_e32 v61, v60
	v_pk_add_f32 v[52:53], v[52:53], 1.0 op_sel_hi:[1,0]
	v_fma_f32 v62, -v60, v61, 1.0
	v_fmac_f32_e32 v61, v62, v61
	v_div_scale_f32 v62, vcc, 1.0, v59, 1.0
	v_mul_f32_e32 v63, v62, v61
	v_fma_f32 v64, -v60, v63, v62
	v_fmac_f32_e32 v63, v64, v61
	v_fma_f32 v60, -v60, v63, v62
	v_div_fmas_f32 v60, v60, v61, v63
	v_div_fixup_f32 v59, v60, v59, 1.0
	v_div_scale_f32 v60, s[16:17], v58, v58, 1.0
	v_rcp_f32_e32 v61, v60
	s_nop 0
	v_fma_f32 v62, -v60, v61, 1.0
	v_fmac_f32_e32 v61, v62, v61
	v_div_scale_f32 v62, vcc, 1.0, v58, 1.0
	v_mul_f32_e32 v63, v62, v61
	v_fma_f32 v64, -v60, v63, v62
	v_fmac_f32_e32 v63, v64, v61
	v_fma_f32 v60, -v60, v63, v62
	v_div_fmas_f32 v60, v60, v61, v63
	v_div_fixup_f32 v58, v60, v58, 1.0
	v_div_scale_f32 v60, s[16:17], v57, v57, 1.0
	v_rcp_f32_e32 v61, v60
	s_nop 0
	v_fma_f32 v62, -v60, v61, 1.0
	v_fmac_f32_e32 v61, v62, v61
	v_div_scale_f32 v62, vcc, 1.0, v57, 1.0
	v_mul_f32_e32 v63, v62, v61
	v_fma_f32 v64, -v60, v63, v62
	v_fmac_f32_e32 v63, v64, v61
	v_fma_f32 v60, -v60, v63, v62
	v_div_fmas_f32 v60, v60, v61, v63
	v_div_fixup_f32 v57, v60, v57, 1.0
	v_div_scale_f32 v60, s[16:17], v56, v56, 1.0
	v_rcp_f32_e32 v61, v60
	s_nop 0
	v_fma_f32 v62, -v60, v61, 1.0
	v_fmac_f32_e32 v61, v62, v61
	v_div_scale_f32 v62, vcc, 1.0, v56, 1.0
	v_mul_f32_e32 v63, v62, v61
	v_fma_f32 v64, -v60, v63, v62
	v_fmac_f32_e32 v63, v64, v61
	v_fma_f32 v60, -v60, v63, v62
	v_div_fmas_f32 v60, v60, v61, v63
	v_div_fixup_f32 v56, v60, v56, 1.0
	v_div_scale_f32 v60, s[16:17], v53, v53, 1.0
	v_rcp_f32_e32 v61, v60
	s_nop 0
	v_fma_f32 v62, -v60, v61, 1.0
	v_fmac_f32_e32 v61, v62, v61
	v_div_scale_f32 v62, vcc, 1.0, v53, 1.0
	v_mul_f32_e32 v63, v62, v61
	v_fma_f32 v64, -v60, v63, v62
	v_fmac_f32_e32 v63, v64, v61
	v_fma_f32 v60, -v60, v63, v62
	v_div_fmas_f32 v60, v60, v61, v63
	v_div_fixup_f32 v53, v60, v53, 1.0
	v_div_scale_f32 v60, s[16:17], v52, v52, 1.0
	v_rcp_f32_e32 v61, v60
	s_mov_b64 s[16:17], 0
	v_fma_f32 v62, -v60, v61, 1.0
	v_fmac_f32_e32 v61, v62, v61
	v_div_scale_f32 v62, vcc, 1.0, v52, 1.0
	v_mul_f32_e32 v63, v62, v61
	v_fma_f32 v64, -v60, v63, v62
	v_fmac_f32_e32 v63, v64, v61
	v_fma_f32 v60, -v60, v63, v62
	v_div_fmas_f32 v60, v60, v61, v63
	v_div_fixup_f32 v52, v60, v52, 1.0
	v_pk_mul_f32 v[62:63], s[18:19], v[52:53] op_sel_hi:[0,1]
	v_pk_mul_f32 v[60:61], s[18:19], v[56:57] op_sel_hi:[0,1]
	v_pk_mul_f32 v[56:57], s[18:19], v[58:59] op_sel_hi:[0,1]
	v_pk_mul_f32 v[52:53], s[18:19], v[54:55] op_sel_hi:[0,1]

.LBB0_1367:
	s_cmp_gt_i32 s19, 3
	s_mov_b64 s[16:17], -1
	s_cbranch_scc0 .LBB0_1369
	v_mov_b32_e32 v42, v190
	v_mov_b32_e32 v43, v191
	v_mov_b32_e32 v44, v192
	v_mov_b32_e32 v45, v193
	v_mov_b32_e32 v46, v186
	v_mov_b32_e32 v47, v187
	v_mov_b32_e32 v48, v188
	v_mov_b32_e32 v49, v189
	v_add_f32_e32 v42, v34, v42
	v_add_f32_e32 v46, v38, v46
	v_mul_f32_e32 v46, 0xbfb8aa3b, v46
	v_exp_f32_e32 v52, v46
	v_add_f32_e32 v46, v39, v47
	v_mul_f32_e32 v46, 0xbfb8aa3b, v46
	v_exp_f32_e32 v53, v46
	v_add_f32_e32 v46, v40, v48
	v_mul_f32_e32 v46, 0xbfb8aa3b, v46
	v_exp_f32_e32 v48, v46
	v_add_f32_e32 v46, v41, v49
	v_mul_f32_e32 v46, 0xbfb8aa3b, v46
	v_mul_f32_e32 v42, 0xbfb8aa3b, v42
	v_exp_f32_e32 v49, v46
	v_exp_f32_e32 v46, v42
	v_add_f32_e32 v42, v35, v43
	v_mul_f32_e32 v42, 0xbfb8aa3b, v42
	v_exp_f32_e32 v47, v42
	v_add_f32_e32 v42, v36, v44
	v_add_f32_e32 v43, v37, v45
	v_pk_add_f32 v[44:45], v[52:53], 1.0 op_sel_hi:[1,0]
	v_pk_add_f32 v[48:49], v[48:49], 1.0 op_sel_hi:[1,0]
	v_div_scale_f32 v52, s[16:17], v45, v45, 1.0
	v_rcp_f32_e32 v53, v52
	v_pk_add_f32 v[46:47], v[46:47], 1.0 op_sel_hi:[1,0]
	v_mul_f32_e32 v42, 0xbfb8aa3b, v42
	v_mul_f32_e32 v43, 0xbfb8aa3b, v43
	v_fma_f32 v54, -v52, v53, 1.0
	v_fmac_f32_e32 v53, v54, v53
	v_div_scale_f32 v54, vcc, 1.0, v45, 1.0
	v_mul_f32_e32 v55, v54, v53
	v_fma_f32 v56, -v52, v55, v54
	v_fmac_f32_e32 v55, v56, v53
	v_fma_f32 v52, -v52, v55, v54
	v_div_fmas_f32 v52, v52, v53, v55
	v_div_fixup_f32 v45, v52, v45, 1.0
	v_div_scale_f32 v52, s[16:17], v44, v44, 1.0
	v_rcp_f32_e32 v53, v52
	v_exp_f32_e32 v42, v42
	v_exp_f32_e32 v43, v43
	v_fma_f32 v54, -v52, v53, 1.0
	v_fmac_f32_e32 v53, v54, v53
	v_div_scale_f32 v54, vcc, 1.0, v44, 1.0
	v_mul_f32_e32 v55, v54, v53
	v_fma_f32 v56, -v52, v55, v54
	v_fmac_f32_e32 v55, v56, v53
	v_fma_f32 v52, -v52, v55, v54
	v_div_fmas_f32 v52, v52, v53, v55
	v_div_fixup_f32 v44, v52, v44, 1.0
	v_div_scale_f32 v52, s[16:17], v49, v49, 1.0
	v_rcp_f32_e32 v53, v52
	v_pk_add_f32 v[42:43], v[42:43], 1.0 op_sel_hi:[1,0]
	v_pk_mul_f32 v[44:45], s[18:19], v[44:45] op_sel_hi:[0,1]
	v_fma_f32 v54, -v52, v53, 1.0
	v_fmac_f32_e32 v53, v54, v53
	v_div_scale_f32 v54, vcc, 1.0, v49, 1.0
	v_mul_f32_e32 v55, v54, v53
	v_fma_f32 v56, -v52, v55, v54
	v_fmac_f32_e32 v55, v56, v53
	v_fma_f32 v52, -v52, v55, v54
	v_div_fmas_f32 v52, v52, v53, v55
	v_div_fixup_f32 v49, v52, v49, 1.0
	v_div_scale_f32 v52, s[16:17], v48, v48, 1.0
	v_rcp_f32_e32 v53, v52
	s_nop 0
	v_fma_f32 v54, -v52, v53, 1.0
	v_fmac_f32_e32 v53, v54, v53
	v_div_scale_f32 v54, vcc, 1.0, v48, 1.0
	v_mul_f32_e32 v55, v54, v53
	v_fma_f32 v56, -v52, v55, v54
	v_fmac_f32_e32 v55, v56, v53
	v_fma_f32 v52, -v52, v55, v54
	v_div_fmas_f32 v52, v52, v53, v55
	v_div_fixup_f32 v48, v52, v48, 1.0
	v_div_scale_f32 v52, s[16:17], v47, v47, 1.0
	v_rcp_f32_e32 v53, v52
	v_pk_mul_f32 v[48:49], s[18:19], v[48:49] op_sel_hi:[0,1]
	v_fma_f32 v54, -v52, v53, 1.0
	v_fmac_f32_e32 v53, v54, v53
	v_div_scale_f32 v54, vcc, 1.0, v47, 1.0
	v_mul_f32_e32 v55, v54, v53
	v_fma_f32 v56, -v52, v55, v54
	v_fmac_f32_e32 v55, v56, v53
	v_fma_f32 v52, -v52, v55, v54
	v_div_fmas_f32 v52, v52, v53, v55
	v_div_fixup_f32 v47, v52, v47, 1.0
	v_div_scale_f32 v52, s[16:17], v46, v46, 1.0
	v_rcp_f32_e32 v53, v52
	s_nop 0
	v_fma_f32 v54, -v52, v53, 1.0
	v_fmac_f32_e32 v53, v54, v53
	v_div_scale_f32 v54, vcc, 1.0, v46, 1.0
	v_mul_f32_e32 v55, v54, v53
	v_fma_f32 v56, -v52, v55, v54
	v_fmac_f32_e32 v55, v56, v53
	v_fma_f32 v52, -v52, v55, v54
	v_div_fmas_f32 v52, v52, v53, v55
	v_div_fixup_f32 v46, v52, v46, 1.0
	v_div_scale_f32 v52, s[16:17], v43, v43, 1.0
	v_rcp_f32_e32 v53, v52
	v_pk_mul_f32 v[46:47], s[18:19], v[46:47] op_sel_hi:[0,1]
	v_fma_f32 v54, -v52, v53, 1.0
	v_fmac_f32_e32 v53, v54, v53
	v_div_scale_f32 v54, vcc, 1.0, v43, 1.0
	v_mul_f32_e32 v55, v54, v53
	v_fma_f32 v56, -v52, v55, v54
	v_fmac_f32_e32 v55, v56, v53
	v_fma_f32 v52, -v52, v55, v54
	v_div_fmas_f32 v52, v52, v53, v55
	v_div_fixup_f32 v43, v52, v43, 1.0
	v_div_scale_f32 v52, s[16:17], v42, v42, 1.0
	v_rcp_f32_e32 v53, v52
	s_nop 0
	v_fma_f32 v54, -v52, v53, 1.0
	v_fmac_f32_e32 v53, v54, v53
	v_div_scale_f32 v54, vcc, 1.0, v42, 1.0
	v_mul_f32_e32 v55, v54, v53
	v_fma_f32 v56, -v52, v55, v54
	v_fmac_f32_e32 v55, v56, v53
	v_fma_f32 v52, -v52, v55, v54
	v_div_fmas_f32 v52, v52, v53, v55
	v_div_fixup_f32 v42, v52, v42, 1.0
	v_pk_mul_f32 v[42:43], s[18:19], v[42:43] op_sel_hi:[0,1]
	s_cbranch_execnz .LBB0_1373
	s_branch .LBB0_1370

.LBB0_1379:
	s_cmp_lt_i32 s5, 3
	s_mov_b64 s[16:17], -1
	s_cbranch_scc1 .LBB0_1385
	s_cmp_gt_i32 s5, 3
	s_cbranch_scc0 .LBB0_1382
	v_mov_b32_e32 v36, v182
	v_mov_b32_e32 v37, v183
	v_mov_b32_e32 v38, v184
	v_mov_b32_e32 v39, v185
	v_mov_b32_e32 v40, v178
	v_mov_b32_e32 v41, v179
	v_mov_b32_e32 v42, v180
	v_mov_b32_e32 v43, v181
	v_add_f32_e32 v36, v26, v36
	v_add_f32_e32 v40, v30, v40
	v_mul_f32_e32 v40, 0xbfb8aa3b, v40
	v_exp_f32_e32 v44, v40
	v_add_f32_e32 v40, v31, v41
	v_mul_f32_e32 v40, 0xbfb8aa3b, v40
	v_exp_f32_e32 v45, v40
	v_add_f32_e32 v40, v32, v42
	v_mul_f32_e32 v40, 0xbfb8aa3b, v40
	v_exp_f32_e32 v42, v40
	v_add_f32_e32 v40, v33, v43
	v_mul_f32_e32 v40, 0xbfb8aa3b, v40
	v_mul_f32_e32 v36, 0xbfb8aa3b, v36
	v_exp_f32_e32 v43, v40
	v_exp_f32_e32 v40, v36
	v_add_f32_e32 v36, v27, v37
	v_mul_f32_e32 v36, 0xbfb8aa3b, v36
	v_exp_f32_e32 v41, v36
	v_add_f32_e32 v36, v28, v38
	v_add_f32_e32 v37, v29, v39
	v_pk_add_f32 v[38:39], v[44:45], 1.0 op_sel_hi:[1,0]
	v_pk_add_f32 v[42:43], v[42:43], 1.0 op_sel_hi:[1,0]
	v_div_scale_f32 v44, s[16:17], v39, v39, 1.0
	v_rcp_f32_e32 v45, v44
	v_pk_add_f32 v[40:41], v[40:41], 1.0 op_sel_hi:[1,0]
	v_mul_f32_e32 v36, 0xbfb8aa3b, v36
	v_mul_f32_e32 v37, 0xbfb8aa3b, v37
	v_fma_f32 v46, -v44, v45, 1.0
	v_fmac_f32_e32 v45, v46, v45
	v_div_scale_f32 v46, vcc, 1.0, v39, 1.0
	v_mul_f32_e32 v47, v46, v45
	v_fma_f32 v48, -v44, v47, v46
	v_fmac_f32_e32 v47, v48, v45
	v_fma_f32 v44, -v44, v47, v46
	v_div_fmas_f32 v44, v44, v45, v47
	v_div_fixup_f32 v39, v44, v39, 1.0
	v_div_scale_f32 v44, s[16:17], v38, v38, 1.0
	v_rcp_f32_e32 v45, v44
	v_exp_f32_e32 v36, v36
	v_exp_f32_e32 v37, v37
	v_fma_f32 v46, -v44, v45, 1.0
	v_fmac_f32_e32 v45, v46, v45
	v_div_scale_f32 v46, vcc, 1.0, v38, 1.0
	v_mul_f32_e32 v47, v46, v45
	v_fma_f32 v48, -v44, v47, v46
	v_fmac_f32_e32 v47, v48, v45
	v_fma_f32 v44, -v44, v47, v46
	v_div_fmas_f32 v44, v44, v45, v47
	v_div_fixup_f32 v38, v44, v38, 1.0
	v_div_scale_f32 v44, s[16:17], v43, v43, 1.0
	v_rcp_f32_e32 v45, v44
	v_pk_add_f32 v[36:37], v[36:37], 1.0 op_sel_hi:[1,0]
	v_fma_f32 v46, -v44, v45, 1.0
	v_fmac_f32_e32 v45, v46, v45
	v_div_scale_f32 v46, vcc, 1.0, v43, 1.0
	v_mul_f32_e32 v47, v46, v45
	v_fma_f32 v48, -v44, v47, v46
	v_fmac_f32_e32 v47, v48, v45
	v_fma_f32 v44, -v44, v47, v46
	v_div_fmas_f32 v44, v44, v45, v47
	v_div_fixup_f32 v43, v44, v43, 1.0
	v_div_scale_f32 v44, s[16:17], v42, v42, 1.0
	v_rcp_f32_e32 v45, v44
	s_nop 0
	v_fma_f32 v46, -v44, v45, 1.0
	v_fmac_f32_e32 v45, v46, v45
	v_div_scale_f32 v46, vcc, 1.0, v42, 1.0
	v_mul_f32_e32 v47, v46, v45
	v_fma_f32 v48, -v44, v47, v46
	v_fmac_f32_e32 v47, v48, v45
	v_fma_f32 v44, -v44, v47, v46
	v_div_fmas_f32 v44, v44, v45, v47
	v_div_fixup_f32 v42, v44, v42, 1.0
	v_div_scale_f32 v44, s[16:17], v41, v41, 1.0
	v_rcp_f32_e32 v45, v44
	s_nop 0
	v_fma_f32 v46, -v44, v45, 1.0
	v_fmac_f32_e32 v45, v46, v45
	v_div_scale_f32 v46, vcc, 1.0, v41, 1.0
	v_mul_f32_e32 v47, v46, v45
	v_fma_f32 v48, -v44, v47, v46
	v_fmac_f32_e32 v47, v48, v45
	v_fma_f32 v44, -v44, v47, v46
	v_div_fmas_f32 v44, v44, v45, v47
	v_div_fixup_f32 v41, v44, v41, 1.0
	v_div_scale_f32 v44, s[16:17], v40, v40, 1.0
	v_rcp_f32_e32 v45, v44
	s_nop 0
	v_fma_f32 v46, -v44, v45, 1.0
	v_fmac_f32_e32 v45, v46, v45
	v_div_scale_f32 v46, vcc, 1.0, v40, 1.0
	v_mul_f32_e32 v47, v46, v45
	v_fma_f32 v48, -v44, v47, v46
	v_fmac_f32_e32 v47, v48, v45
	v_fma_f32 v44, -v44, v47, v46
	v_div_fmas_f32 v44, v44, v45, v47
	v_div_fixup_f32 v40, v44, v40, 1.0
	v_div_scale_f32 v44, s[16:17], v37, v37, 1.0
	v_rcp_f32_e32 v45, v44
	s_nop 0
	v_fma_f32 v46, -v44, v45, 1.0
	v_fmac_f32_e32 v45, v46, v45
	v_div_scale_f32 v46, vcc, 1.0, v37, 1.0
	v_mul_f32_e32 v47, v46, v45
	v_fma_f32 v48, -v44, v47, v46
	v_fmac_f32_e32 v47, v48, v45
	v_fma_f32 v44, -v44, v47, v46
	v_div_fmas_f32 v44, v44, v45, v47
	v_div_fixup_f32 v37, v44, v37, 1.0
	v_div_scale_f32 v44, s[16:17], v36, v36, 1.0
	v_rcp_f32_e32 v45, v44
	s_mov_b64 s[16:17], 0
	v_fma_f32 v46, -v44, v45, 1.0
	v_fmac_f32_e32 v45, v46, v45
	v_div_scale_f32 v46, vcc, 1.0, v36, 1.0
	v_mul_f32_e32 v47, v46, v45
	v_fma_f32 v48, -v44, v47, v46
	v_fmac_f32_e32 v47, v48, v45
	v_fma_f32 v44, -v44, v47, v46
	v_div_fmas_f32 v44, v44, v45, v47
	v_div_fixup_f32 v36, v44, v36, 1.0
	v_pk_mul_f32 v[46:47], s[18:19], v[36:37] op_sel_hi:[0,1]
	v_pk_mul_f32 v[44:45], s[18:19], v[40:41] op_sel_hi:[0,1]
	v_pk_mul_f32 v[40:41], s[18:19], v[42:43] op_sel_hi:[0,1]
	v_pk_mul_f32 v[36:37], s[18:19], v[38:39] op_sel_hi:[0,1]

.LBB0_1395:
	s_cmp_gt_i32 s19, 3
	s_mov_b64 s[16:17], -1
	s_cbranch_scc0 .LBB0_1397
	v_mov_b32_e32 v26, v190
	v_mov_b32_e32 v27, v191
	v_mov_b32_e32 v28, v192
	v_mov_b32_e32 v29, v193
	v_mov_b32_e32 v30, v186
	v_mov_b32_e32 v31, v187
	v_mov_b32_e32 v32, v188
	v_mov_b32_e32 v33, v189
	v_add_f32_e32 v26, v18, v26
	v_add_f32_e32 v30, v22, v30
	v_mul_f32_e32 v30, 0xbfb8aa3b, v30
	v_exp_f32_e32 v36, v30
	v_add_f32_e32 v30, v23, v31
	v_mul_f32_e32 v30, 0xbfb8aa3b, v30
	v_exp_f32_e32 v37, v30
	v_add_f32_e32 v30, v24, v32
	v_mul_f32_e32 v30, 0xbfb8aa3b, v30
	v_exp_f32_e32 v32, v30
	v_add_f32_e32 v30, v25, v33
	v_mul_f32_e32 v30, 0xbfb8aa3b, v30
	v_mul_f32_e32 v26, 0xbfb8aa3b, v26
	v_exp_f32_e32 v33, v30
	v_exp_f32_e32 v30, v26
	v_add_f32_e32 v26, v19, v27
	v_mul_f32_e32 v26, 0xbfb8aa3b, v26
	v_exp_f32_e32 v31, v26
	v_add_f32_e32 v26, v20, v28
	v_add_f32_e32 v27, v21, v29
	v_pk_add_f32 v[28:29], v[36:37], 1.0 op_sel_hi:[1,0]
	v_pk_add_f32 v[32:33], v[32:33], 1.0 op_sel_hi:[1,0]
	v_div_scale_f32 v36, s[16:17], v29, v29, 1.0
	v_rcp_f32_e32 v37, v36
	v_pk_add_f32 v[30:31], v[30:31], 1.0 op_sel_hi:[1,0]
	v_mul_f32_e32 v26, 0xbfb8aa3b, v26
	v_mul_f32_e32 v27, 0xbfb8aa3b, v27
	v_fma_f32 v38, -v36, v37, 1.0
	v_fmac_f32_e32 v37, v38, v37
	v_div_scale_f32 v38, vcc, 1.0, v29, 1.0
	v_mul_f32_e32 v39, v38, v37
	v_fma_f32 v40, -v36, v39, v38
	v_fmac_f32_e32 v39, v40, v37
	v_fma_f32 v36, -v36, v39, v38
	v_div_fmas_f32 v36, v36, v37, v39
	v_div_fixup_f32 v29, v36, v29, 1.0
	v_div_scale_f32 v36, s[16:17], v28, v28, 1.0
	v_rcp_f32_e32 v37, v36
	v_exp_f32_e32 v26, v26
	v_exp_f32_e32 v27, v27
	v_fma_f32 v38, -v36, v37, 1.0
	v_fmac_f32_e32 v37, v38, v37
	v_div_scale_f32 v38, vcc, 1.0, v28, 1.0
	v_mul_f32_e32 v39, v38, v37
	v_fma_f32 v40, -v36, v39, v38
	v_fmac_f32_e32 v39, v40, v37
	v_fma_f32 v36, -v36, v39, v38
	v_div_fmas_f32 v36, v36, v37, v39
	v_div_fixup_f32 v28, v36, v28, 1.0
	v_div_scale_f32 v36, s[16:17], v33, v33, 1.0
	v_rcp_f32_e32 v37, v36
	v_pk_add_f32 v[26:27], v[26:27], 1.0 op_sel_hi:[1,0]
	v_pk_mul_f32 v[28:29], s[18:19], v[28:29] op_sel_hi:[0,1]
	v_fma_f32 v38, -v36, v37, 1.0
	v_fmac_f32_e32 v37, v38, v37
	v_div_scale_f32 v38, vcc, 1.0, v33, 1.0
	v_mul_f32_e32 v39, v38, v37
	v_fma_f32 v40, -v36, v39, v38
	v_fmac_f32_e32 v39, v40, v37
	v_fma_f32 v36, -v36, v39, v38
	v_div_fmas_f32 v36, v36, v37, v39
	v_div_fixup_f32 v33, v36, v33, 1.0
	v_div_scale_f32 v36, s[16:17], v32, v32, 1.0
	v_rcp_f32_e32 v37, v36
	s_nop 0
	v_fma_f32 v38, -v36, v37, 1.0
	v_fmac_f32_e32 v37, v38, v37
	v_div_scale_f32 v38, vcc, 1.0, v32, 1.0
	v_mul_f32_e32 v39, v38, v37
	v_fma_f32 v40, -v36, v39, v38
	v_fmac_f32_e32 v39, v40, v37
	v_fma_f32 v36, -v36, v39, v38
	v_div_fmas_f32 v36, v36, v37, v39
	v_div_fixup_f32 v32, v36, v32, 1.0
	v_div_scale_f32 v36, s[16:17], v31, v31, 1.0
	v_rcp_f32_e32 v37, v36
	v_pk_mul_f32 v[32:33], s[18:19], v[32:33] op_sel_hi:[0,1]
	v_fma_f32 v38, -v36, v37, 1.0
	v_fmac_f32_e32 v37, v38, v37
	v_div_scale_f32 v38, vcc, 1.0, v31, 1.0
	v_mul_f32_e32 v39, v38, v37
	v_fma_f32 v40, -v36, v39, v38
	v_fmac_f32_e32 v39, v40, v37
	v_fma_f32 v36, -v36, v39, v38
	v_div_fmas_f32 v36, v36, v37, v39
	v_div_fixup_f32 v31, v36, v31, 1.0
	v_div_scale_f32 v36, s[16:17], v30, v30, 1.0
	v_rcp_f32_e32 v37, v36
	s_nop 0
	v_fma_f32 v38, -v36, v37, 1.0
	v_fmac_f32_e32 v37, v38, v37
	v_div_scale_f32 v38, vcc, 1.0, v30, 1.0
	v_mul_f32_e32 v39, v38, v37
	v_fma_f32 v40, -v36, v39, v38
	v_fmac_f32_e32 v39, v40, v37
	v_fma_f32 v36, -v36, v39, v38
	v_div_fmas_f32 v36, v36, v37, v39
	v_div_fixup_f32 v30, v36, v30, 1.0
	v_div_scale_f32 v36, s[16:17], v27, v27, 1.0
	v_rcp_f32_e32 v37, v36
	v_pk_mul_f32 v[30:31], s[18:19], v[30:31] op_sel_hi:[0,1]
	v_fma_f32 v38, -v36, v37, 1.0
	v_fmac_f32_e32 v37, v38, v37
	v_div_scale_f32 v38, vcc, 1.0, v27, 1.0
	v_mul_f32_e32 v39, v38, v37
	v_fma_f32 v40, -v36, v39, v38
	v_fmac_f32_e32 v39, v40, v37
	v_fma_f32 v36, -v36, v39, v38
	v_div_fmas_f32 v36, v36, v37, v39
	v_div_fixup_f32 v27, v36, v27, 1.0
	v_div_scale_f32 v36, s[16:17], v26, v26, 1.0
	v_rcp_f32_e32 v37, v36
	s_nop 0
	v_fma_f32 v38, -v36, v37, 1.0
	v_fmac_f32_e32 v37, v38, v37
	v_div_scale_f32 v38, vcc, 1.0, v26, 1.0
	v_mul_f32_e32 v39, v38, v37
	v_fma_f32 v40, -v36, v39, v38
	v_fmac_f32_e32 v39, v40, v37
	v_fma_f32 v36, -v36, v39, v38
	v_div_fmas_f32 v36, v36, v37, v39
	v_div_fixup_f32 v26, v36, v26, 1.0
	v_pk_mul_f32 v[26:27], s[18:19], v[26:27] op_sel_hi:[0,1]
	s_cbranch_execnz .LBB0_1401
	s_branch .LBB0_1398

.LBB0_1407:
	s_cmp_lt_i32 s5, 3
	s_mov_b64 s[16:17], -1
	s_cbranch_scc1 .LBB0_1413
	s_cmp_gt_i32 s5, 3
	s_cbranch_scc0 .LBB0_1410
	v_mov_b32_e32 v20, v182
	v_mov_b32_e32 v21, v183
	v_mov_b32_e32 v22, v184
	v_mov_b32_e32 v23, v185
	v_mov_b32_e32 v24, v178
	v_mov_b32_e32 v25, v179
	v_mov_b32_e32 v26, v180
	v_mov_b32_e32 v27, v181
	v_add_f32_e32 v20, v10, v20
	v_add_f32_e32 v24, v14, v24
	v_mul_f32_e32 v24, 0xbfb8aa3b, v24
	v_exp_f32_e32 v28, v24
	v_add_f32_e32 v24, v15, v25
	v_mul_f32_e32 v24, 0xbfb8aa3b, v24
	v_exp_f32_e32 v29, v24
	v_add_f32_e32 v24, v16, v26
	v_mul_f32_e32 v24, 0xbfb8aa3b, v24
	v_exp_f32_e32 v26, v24
	v_add_f32_e32 v24, v17, v27
	v_mul_f32_e32 v24, 0xbfb8aa3b, v24
	v_mul_f32_e32 v20, 0xbfb8aa3b, v20
	v_exp_f32_e32 v27, v24
	v_exp_f32_e32 v24, v20
	v_add_f32_e32 v20, v11, v21
	v_mul_f32_e32 v20, 0xbfb8aa3b, v20
	v_exp_f32_e32 v25, v20
	v_add_f32_e32 v20, v12, v22
	v_add_f32_e32 v21, v13, v23
	v_pk_add_f32 v[22:23], v[28:29], 1.0 op_sel_hi:[1,0]
	v_pk_add_f32 v[26:27], v[26:27], 1.0 op_sel_hi:[1,0]
	v_div_scale_f32 v28, s[16:17], v23, v23, 1.0
	v_rcp_f32_e32 v29, v28
	v_pk_add_f32 v[24:25], v[24:25], 1.0 op_sel_hi:[1,0]
	v_mul_f32_e32 v20, 0xbfb8aa3b, v20
	v_mul_f32_e32 v21, 0xbfb8aa3b, v21
	v_fma_f32 v30, -v28, v29, 1.0
	v_fmac_f32_e32 v29, v30, v29
	v_div_scale_f32 v30, vcc, 1.0, v23, 1.0
	v_mul_f32_e32 v31, v30, v29
	v_fma_f32 v32, -v28, v31, v30
	v_fmac_f32_e32 v31, v32, v29
	v_fma_f32 v28, -v28, v31, v30
	v_div_fmas_f32 v28, v28, v29, v31
	v_div_fixup_f32 v23, v28, v23, 1.0
	v_div_scale_f32 v28, s[16:17], v22, v22, 1.0
	v_rcp_f32_e32 v29, v28
	v_exp_f32_e32 v20, v20
	v_exp_f32_e32 v21, v21
	v_fma_f32 v30, -v28, v29, 1.0
	v_fmac_f32_e32 v29, v30, v29
	v_div_scale_f32 v30, vcc, 1.0, v22, 1.0
	v_mul_f32_e32 v31, v30, v29
	v_fma_f32 v32, -v28, v31, v30
	v_fmac_f32_e32 v31, v32, v29
	v_fma_f32 v28, -v28, v31, v30
	v_div_fmas_f32 v28, v28, v29, v31
	v_div_fixup_f32 v22, v28, v22, 1.0
	v_div_scale_f32 v28, s[16:17], v27, v27, 1.0
	v_rcp_f32_e32 v29, v28
	v_pk_add_f32 v[20:21], v[20:21], 1.0 op_sel_hi:[1,0]
	v_fma_f32 v30, -v28, v29, 1.0
	v_fmac_f32_e32 v29, v30, v29
	v_div_scale_f32 v30, vcc, 1.0, v27, 1.0
	v_mul_f32_e32 v31, v30, v29
	v_fma_f32 v32, -v28, v31, v30
	v_fmac_f32_e32 v31, v32, v29
	v_fma_f32 v28, -v28, v31, v30
	v_div_fmas_f32 v28, v28, v29, v31
	v_div_fixup_f32 v27, v28, v27, 1.0
	v_div_scale_f32 v28, s[16:17], v26, v26, 1.0
	v_rcp_f32_e32 v29, v28
	s_nop 0
	v_fma_f32 v30, -v28, v29, 1.0
	v_fmac_f32_e32 v29, v30, v29
	v_div_scale_f32 v30, vcc, 1.0, v26, 1.0
	v_mul_f32_e32 v31, v30, v29
	v_fma_f32 v32, -v28, v31, v30
	v_fmac_f32_e32 v31, v32, v29
	v_fma_f32 v28, -v28, v31, v30
	v_div_fmas_f32 v28, v28, v29, v31
	v_div_fixup_f32 v26, v28, v26, 1.0
	v_div_scale_f32 v28, s[16:17], v25, v25, 1.0
	v_rcp_f32_e32 v29, v28
	s_nop 0
	v_fma_f32 v30, -v28, v29, 1.0
	v_fmac_f32_e32 v29, v30, v29
	v_div_scale_f32 v30, vcc, 1.0, v25, 1.0
	v_mul_f32_e32 v31, v30, v29
	v_fma_f32 v32, -v28, v31, v30
	v_fmac_f32_e32 v31, v32, v29
	v_fma_f32 v28, -v28, v31, v30
	v_div_fmas_f32 v28, v28, v29, v31
	v_div_fixup_f32 v25, v28, v25, 1.0
	v_div_scale_f32 v28, s[16:17], v24, v24, 1.0
	v_rcp_f32_e32 v29, v28
	s_nop 0
	v_fma_f32 v30, -v28, v29, 1.0
	v_fmac_f32_e32 v29, v30, v29
	v_div_scale_f32 v30, vcc, 1.0, v24, 1.0
	v_mul_f32_e32 v31, v30, v29
	v_fma_f32 v32, -v28, v31, v30
	v_fmac_f32_e32 v31, v32, v29
	v_fma_f32 v28, -v28, v31, v30
	v_div_fmas_f32 v28, v28, v29, v31
	v_div_fixup_f32 v24, v28, v24, 1.0
	v_div_scale_f32 v28, s[16:17], v21, v21, 1.0
	v_rcp_f32_e32 v29, v28
	s_nop 0
	v_fma_f32 v30, -v28, v29, 1.0
	v_fmac_f32_e32 v29, v30, v29
	v_div_scale_f32 v30, vcc, 1.0, v21, 1.0
	v_mul_f32_e32 v31, v30, v29
	v_fma_f32 v32, -v28, v31, v30
	v_fmac_f32_e32 v31, v32, v29
	v_fma_f32 v28, -v28, v31, v30
	v_div_fmas_f32 v28, v28, v29, v31
	v_div_fixup_f32 v21, v28, v21, 1.0
	v_div_scale_f32 v28, s[16:17], v20, v20, 1.0
	v_rcp_f32_e32 v29, v28
	s_mov_b64 s[16:17], 0
	v_fma_f32 v30, -v28, v29, 1.0
	v_fmac_f32_e32 v29, v30, v29
	v_div_scale_f32 v30, vcc, 1.0, v20, 1.0
	v_mul_f32_e32 v31, v30, v29
	v_fma_f32 v32, -v28, v31, v30
	v_fmac_f32_e32 v31, v32, v29
	v_fma_f32 v28, -v28, v31, v30
	v_div_fmas_f32 v28, v28, v29, v31
	v_div_fixup_f32 v20, v28, v20, 1.0
	v_pk_mul_f32 v[30:31], s[18:19], v[20:21] op_sel_hi:[0,1]
	v_pk_mul_f32 v[28:29], s[18:19], v[24:25] op_sel_hi:[0,1]
	v_pk_mul_f32 v[24:25], s[18:19], v[26:27] op_sel_hi:[0,1]
	v_pk_mul_f32 v[20:21], s[18:19], v[22:23] op_sel_hi:[0,1]

.LBB0_1423:
	s_cmp_gt_i32 s19, 3
	s_mov_b64 s[16:17], -1
	s_cbranch_scc0 .LBB0_1425
	v_mov_b32_e32 v10, v190
	v_mov_b32_e32 v11, v191
	v_mov_b32_e32 v12, v192
	v_mov_b32_e32 v13, v193
	v_mov_b32_e32 v14, v186
	v_mov_b32_e32 v15, v187
	v_mov_b32_e32 v16, v188
	v_mov_b32_e32 v17, v189
	v_add_f32_e32 v10, v2, v10
	v_add_f32_e32 v14, v6, v14
	v_mul_f32_e32 v14, 0xbfb8aa3b, v14
	v_exp_f32_e32 v20, v14
	v_add_f32_e32 v14, v7, v15
	v_mul_f32_e32 v14, 0xbfb8aa3b, v14
	v_exp_f32_e32 v21, v14
	v_add_f32_e32 v14, v8, v16
	v_mul_f32_e32 v14, 0xbfb8aa3b, v14
	v_exp_f32_e32 v16, v14
	v_add_f32_e32 v14, v9, v17
	v_mul_f32_e32 v14, 0xbfb8aa3b, v14
	v_mul_f32_e32 v10, 0xbfb8aa3b, v10
	v_exp_f32_e32 v17, v14
	v_exp_f32_e32 v14, v10
	v_add_f32_e32 v10, v3, v11
	v_mul_f32_e32 v10, 0xbfb8aa3b, v10
	v_exp_f32_e32 v15, v10
	v_add_f32_e32 v10, v4, v12
	v_add_f32_e32 v11, v5, v13
	v_pk_add_f32 v[12:13], v[20:21], 1.0 op_sel_hi:[1,0]
	v_pk_add_f32 v[16:17], v[16:17], 1.0 op_sel_hi:[1,0]
	v_div_scale_f32 v20, s[16:17], v13, v13, 1.0
	v_rcp_f32_e32 v21, v20
	v_pk_add_f32 v[14:15], v[14:15], 1.0 op_sel_hi:[1,0]
	v_mul_f32_e32 v10, 0xbfb8aa3b, v10
	v_mul_f32_e32 v11, 0xbfb8aa3b, v11
	v_fma_f32 v22, -v20, v21, 1.0
	v_fmac_f32_e32 v21, v22, v21
	v_div_scale_f32 v22, vcc, 1.0, v13, 1.0
	v_mul_f32_e32 v23, v22, v21
	v_fma_f32 v24, -v20, v23, v22
	v_fmac_f32_e32 v23, v24, v21
	v_fma_f32 v20, -v20, v23, v22
	v_div_fmas_f32 v20, v20, v21, v23
	v_div_fixup_f32 v13, v20, v13, 1.0
	v_div_scale_f32 v20, s[16:17], v12, v12, 1.0
	v_rcp_f32_e32 v21, v20
	v_exp_f32_e32 v10, v10
	v_exp_f32_e32 v11, v11
	v_fma_f32 v22, -v20, v21, 1.0
	v_fmac_f32_e32 v21, v22, v21
	v_div_scale_f32 v22, vcc, 1.0, v12, 1.0
	v_mul_f32_e32 v23, v22, v21
	v_fma_f32 v24, -v20, v23, v22
	v_fmac_f32_e32 v23, v24, v21
	v_fma_f32 v20, -v20, v23, v22
	v_div_fmas_f32 v20, v20, v21, v23
	v_div_fixup_f32 v12, v20, v12, 1.0
	v_div_scale_f32 v20, s[16:17], v17, v17, 1.0
	v_rcp_f32_e32 v21, v20
	v_pk_add_f32 v[10:11], v[10:11], 1.0 op_sel_hi:[1,0]
	v_pk_mul_f32 v[12:13], s[18:19], v[12:13] op_sel_hi:[0,1]
	v_fma_f32 v22, -v20, v21, 1.0
	v_fmac_f32_e32 v21, v22, v21
	v_div_scale_f32 v22, vcc, 1.0, v17, 1.0
	v_mul_f32_e32 v23, v22, v21
	v_fma_f32 v24, -v20, v23, v22
	v_fmac_f32_e32 v23, v24, v21
	v_fma_f32 v20, -v20, v23, v22
	v_div_fmas_f32 v20, v20, v21, v23
	v_div_fixup_f32 v17, v20, v17, 1.0
	v_div_scale_f32 v20, s[16:17], v16, v16, 1.0
	v_rcp_f32_e32 v21, v20
	s_nop 0
	v_fma_f32 v22, -v20, v21, 1.0
	v_fmac_f32_e32 v21, v22, v21
	v_div_scale_f32 v22, vcc, 1.0, v16, 1.0
	v_mul_f32_e32 v23, v22, v21
	v_fma_f32 v24, -v20, v23, v22
	v_fmac_f32_e32 v23, v24, v21
	v_fma_f32 v20, -v20, v23, v22
	v_div_fmas_f32 v20, v20, v21, v23
	v_div_fixup_f32 v16, v20, v16, 1.0
	v_div_scale_f32 v20, s[16:17], v15, v15, 1.0
	v_rcp_f32_e32 v21, v20
	v_pk_mul_f32 v[16:17], s[18:19], v[16:17] op_sel_hi:[0,1]
	v_fma_f32 v22, -v20, v21, 1.0
	v_fmac_f32_e32 v21, v22, v21
	v_div_scale_f32 v22, vcc, 1.0, v15, 1.0
	v_mul_f32_e32 v23, v22, v21
	v_fma_f32 v24, -v20, v23, v22
	v_fmac_f32_e32 v23, v24, v21
	v_fma_f32 v20, -v20, v23, v22
	v_div_fmas_f32 v20, v20, v21, v23
	v_div_fixup_f32 v15, v20, v15, 1.0
	v_div_scale_f32 v20, s[16:17], v14, v14, 1.0
	v_rcp_f32_e32 v21, v20
	s_nop 0
	v_fma_f32 v22, -v20, v21, 1.0
	v_fmac_f32_e32 v21, v22, v21
	v_div_scale_f32 v22, vcc, 1.0, v14, 1.0
	v_mul_f32_e32 v23, v22, v21
	v_fma_f32 v24, -v20, v23, v22
	v_fmac_f32_e32 v23, v24, v21
	v_fma_f32 v20, -v20, v23, v22
	v_div_fmas_f32 v20, v20, v21, v23
	v_div_fixup_f32 v14, v20, v14, 1.0
	v_div_scale_f32 v20, s[16:17], v11, v11, 1.0
	v_rcp_f32_e32 v21, v20
	v_pk_mul_f32 v[14:15], s[18:19], v[14:15] op_sel_hi:[0,1]
	v_fma_f32 v22, -v20, v21, 1.0
	v_fmac_f32_e32 v21, v22, v21
	v_div_scale_f32 v22, vcc, 1.0, v11, 1.0
	v_mul_f32_e32 v23, v22, v21
	v_fma_f32 v24, -v20, v23, v22
	v_fmac_f32_e32 v23, v24, v21
	v_fma_f32 v20, -v20, v23, v22
	v_div_fmas_f32 v20, v20, v21, v23
	v_div_fixup_f32 v11, v20, v11, 1.0
	v_div_scale_f32 v20, s[16:17], v10, v10, 1.0
	v_rcp_f32_e32 v21, v20
	s_nop 0
	v_fma_f32 v22, -v20, v21, 1.0
	v_fmac_f32_e32 v21, v22, v21
	v_div_scale_f32 v22, vcc, 1.0, v10, 1.0
	v_mul_f32_e32 v23, v22, v21
	v_fma_f32 v24, -v20, v23, v22
	v_fmac_f32_e32 v23, v24, v21
	v_fma_f32 v20, -v20, v23, v22
	v_div_fmas_f32 v20, v20, v21, v23
	v_div_fixup_f32 v10, v20, v10, 1.0
	v_pk_mul_f32 v[10:11], s[18:19], v[10:11] op_sel_hi:[0,1]
	s_cbranch_execnz .LBB0_1429
	s_branch .LBB0_1426
